# adds: P0 row conversion fast path (all 8 rows of a wave requested up front, stores behind counted waits, batched reductions)
# baseline (speedup 1.0000x reference)
; __device__ __forceinline__ unsigned pk2(float lo, float hi) { return pg8::cvt_pk_bf16(lo, hi); }
; __device__ __forceinline__ void wt_store16(const WsRef& w, const void* p, u32x4 v) { __builtin_amdgcn_raw_buffer_store_b128(v, w.r, (unsigned)((const unsigned char*)p - w.base), 0, 16); }
; __global__ void __launch_bounds__(512, 2) fwd_mega(Args a) {
;     ...
;         for (int m = gw; m < M; m += 2 * NGW) {
;             const int m2 = (m + NGW < M) ? m + NGW : m;
;             const f32x4* xr0 = (const f32x4*)(x + (size_t)m * D) + 2 * lane; const f32x4* xr1 = (const f32x4*)(x + (size_t)m2 * D) + 2 * lane;
;             f32x4 v0[4], v1[4]; float s0 = 0.f, s1 = 0.f;
; #pragma unroll
;             for (int j = 0; j < 2; ++j) { v0[2 * j] = xr0[128 * j]; v0[2 * j + 1] = xr0[128 * j + 1]; v1[2 * j] = xr1[128 * j]; v1[2 * j + 1] = xr1[128 * j + 1]; }
; #pragma unroll
;             for (int j = 0; j < 4; ++j) { s0 += (v0[j].x * v0[j].x + v0[j].y * v0[j].y) + (v0[j].z * v0[j].z + v0[j].w * v0[j].w); s1 += (v1[j].x * v1[j].x + v1[j].y * v1[j].y) + (v1[j].z * v1[j].z + v1[j].w * v1[j].w); }
; #pragma unroll
;             for (int o = 1; o < 64; o <<= 1) { s0 += __shfl_xor(s0, o); s1 += __shfl_xor(s1, o); }
;             if (lane == 0) { RSQX[m] = s0; RSQX[m2] = s1; }
;             bf16* o0 = H + (size_t)m * D + 8 * lane; bf16* o1 = H + (size_t)m2 * D + 8 * lane;
; #pragma unroll
;             for (int j = 0; j < 2; ++j) { const f32x4 a0 = v0[2 * j], b0 = v0[2 * j + 1], a1 = v1[2 * j], b1 = v1[2 * j + 1];
;                 u32x4 p0, p1; p0.x = pk2(a0.x, a0.y); p0.y = pk2(a0.z, a0.w); p0.z = pk2(b0.x, b0.y); p0.w = pk2(b0.z, b0.w); p1.x = pk2(a1.x, a1.y); p1.y = pk2(a1.z, a1.w); p1.z = pk2(b1.x, b1.y); p1.w = pk2(b1.z, b1.w);
;                 wt_store16(wsr, o0 + 512 * j, p0); if (m2 != m) wt_store16(wsr, o1 + 512 * j, p1); }
;         }
.LBB0_57:
	v_readlane_b32 s0, v255, 6
	s_cmpk_gt_i32 s0, 0x3fff
	v_readlane_b32 s1, v255, 7
	s_cbranch_scc1 .LBB0_66
	v_mbcnt_lo_u32_b32 v0, -1, 0
	v_mbcnt_hi_u32_b32 v0, -1, v0
	v_and_b32_e32 v1, 64, v0
	v_add_u32_e32 v1, 64, v1
	v_xor_b32_e32 v2, 1, v0
	v_lshlrev_b32_e32 v32, 5, v204
	v_mov_b32_e32 v33, 0
	v_cmp_lt_i32_e32 vcc, v2, v1
	s_waitcnt lgkmcnt(0)
	v_lshl_add_u64 v[34:35], s[8:9], 0, v[32:33]
	v_lshlrev_b32_e32 v32, 4, v204
	v_cndmask_b32_e32 v2, v0, v2, vcc
	v_lshl_add_u64 v[36:37], s[96:97], 0, v[32:33]
	v_lshlrev_b32_e32 v32, 2, v2
	v_xor_b32_e32 v2, 2, v0
	v_cmp_lt_i32_e32 vcc, v2, v1
	v_cmp_eq_u32_e64 s[0:1], 0, v204
	s_mov_b32 s88, s84
	v_cndmask_b32_e32 v2, v0, v2, vcc
	v_lshlrev_b32_e32 v38, 2, v2
	v_xor_b32_e32 v2, 4, v0
	v_cmp_lt_i32_e32 vcc, v2, v1
	v_readlane_b32 s6, v255, 6
	v_readlane_b32 s7, v255, 7
	v_cndmask_b32_e32 v2, v0, v2, vcc
	v_lshlrev_b32_e32 v39, 2, v2
	v_xor_b32_e32 v2, 8, v0
	v_cmp_lt_i32_e32 vcc, v2, v1
	s_nop 1
	v_cndmask_b32_e32 v2, v0, v2, vcc
	v_lshlrev_b32_e32 v40, 2, v2
	v_xor_b32_e32 v2, 16, v0
	v_cmp_lt_i32_e32 vcc, v2, v1
	s_nop 1
	v_cndmask_b32_e32 v2, v0, v2, vcc
	v_lshlrev_b32_e32 v41, 2, v2
	v_xor_b32_e32 v2, 32, v0
	v_cmp_lt_i32_e32 vcc, v2, v1
	s_nop 1
	v_cndmask_b32_e32 v0, v0, v2, vcc
	v_lshlrev_b32_e32 v42, 2, v0
	s_cmpk_eq_i32 s80, 0x800
	s_cbranch_scc0 .LBB0_60
	v_subrev_u32_e32 v43, s84, v36
	s_mov_b32 s3, s6
	s_mov_b32 s15, 0
	s_lshl_b32 s14, s3, 12
	s_add_i32 s3, s3, s80
	v_lshl_add_u64 v[0:1], v[34:35], 0, s[14:15]
	global_load_dwordx4 v[48:51], v[0:1], off
	global_load_dwordx4 v[52:55], v[0:1], off offset:16
	global_load_dwordx4 v[56:59], v[0:1], off offset:2048
	global_load_dwordx4 v[60:63], v[0:1], off offset:2064
	s_lshl_b32 s14, s3, 12
	s_add_i32 s3, s3, s80
	v_lshl_add_u64 v[0:1], v[34:35], 0, s[14:15]
	global_load_dwordx4 v[64:67], v[0:1], off
	global_load_dwordx4 v[68:71], v[0:1], off offset:16
	global_load_dwordx4 v[72:75], v[0:1], off offset:2048
	global_load_dwordx4 v[76:79], v[0:1], off offset:2064
	s_lshl_b32 s14, s3, 12
	s_add_i32 s3, s3, s80
	v_lshl_add_u64 v[0:1], v[34:35], 0, s[14:15]
	global_load_dwordx4 v[80:83], v[0:1], off
	global_load_dwordx4 v[84:87], v[0:1], off offset:16
	global_load_dwordx4 v[88:91], v[0:1], off offset:2048
	global_load_dwordx4 v[92:95], v[0:1], off offset:2064
	s_lshl_b32 s14, s3, 12
	s_add_i32 s3, s3, s80
	v_lshl_add_u64 v[0:1], v[34:35], 0, s[14:15]
	global_load_dwordx4 v[96:99], v[0:1], off
	global_load_dwordx4 v[100:103], v[0:1], off offset:16
	global_load_dwordx4 v[104:107], v[0:1], off offset:2048
	global_load_dwordx4 v[108:111], v[0:1], off offset:2064
	s_lshl_b32 s14, s3, 12
	s_add_i32 s3, s3, s80
	v_lshl_add_u64 v[0:1], v[34:35], 0, s[14:15]
	global_load_dwordx4 v[112:115], v[0:1], off
	global_load_dwordx4 v[116:119], v[0:1], off offset:16
	global_load_dwordx4 v[120:123], v[0:1], off offset:2048
	global_load_dwordx4 v[124:127], v[0:1], off offset:2064
	s_lshl_b32 s14, s3, 12
	s_add_i32 s3, s3, s80
	v_lshl_add_u64 v[0:1], v[34:35], 0, s[14:15]
	global_load_dwordx4 v[130:133], v[0:1], off
	global_load_dwordx4 v[134:137], v[0:1], off offset:16
	global_load_dwordx4 v[138:141], v[0:1], off offset:2048
	global_load_dwordx4 v[142:145], v[0:1], off offset:2064
	s_lshl_b32 s14, s3, 12
	s_add_i32 s3, s3, s80
	v_lshl_add_u64 v[0:1], v[34:35], 0, s[14:15]
	global_load_dwordx4 v[146:149], v[0:1], off
	global_load_dwordx4 v[150:153], v[0:1], off offset:16
	global_load_dwordx4 v[154:157], v[0:1], off offset:2048
	global_load_dwordx4 v[158:161], v[0:1], off offset:2064
	s_lshl_b32 s14, s3, 12
	s_add_i32 s3, s3, s80
	v_lshl_add_u64 v[0:1], v[34:35], 0, s[14:15]
	global_load_dwordx4 v[162:165], v[0:1], off
	global_load_dwordx4 v[166:169], v[0:1], off offset:16
	global_load_dwordx4 v[170:173], v[0:1], off offset:2048
	global_load_dwordx4 v[174:177], v[0:1], off offset:2064
	s_mov_b32 s3, s6
	s_waitcnt vmcnt(28)
	v_mul_f32_e32 v45, v49, v49
	v_mul_f32_e32 v46, v51, v51
	v_fmac_f32_e32 v45, v48, v48
	v_fmac_f32_e32 v46, v50, v50
	v_add_f32_e32 v180, v45, v46
	v_mul_f32_e32 v45, v53, v53
	v_mul_f32_e32 v46, v55, v55
	v_fmac_f32_e32 v45, v52, v52
	v_fmac_f32_e32 v46, v54, v54
	v_add_f32_e32 v47, v45, v46
	v_add_f32_e32 v180, v180, v47
	v_mul_f32_e32 v45, v57, v57
	v_mul_f32_e32 v46, v59, v59
	v_fmac_f32_e32 v45, v56, v56
	v_fmac_f32_e32 v46, v58, v58
	v_add_f32_e32 v47, v45, v46
	v_add_f32_e32 v180, v180, v47
	v_mul_f32_e32 v45, v61, v61
	v_mul_f32_e32 v46, v63, v63
	v_fmac_f32_e32 v45, v60, v60
	v_fmac_f32_e32 v46, v62, v62
	v_add_f32_e32 v47, v45, v46
	v_add_f32_e32 v180, v180, v47
	s_lshl_b32 s14, s3, 11
	s_add_i32 s3, s3, s80
	v_add_u32_e32 v44, s14, v43
	v_cvt_pk_bf16_f32 v48, v48, v49
	v_cvt_pk_bf16_f32 v49, v50, v51
	v_cvt_pk_bf16_f32 v50, v52, v53
	v_cvt_pk_bf16_f32 v51, v54, v55
	buffer_store_dwordx4 v[48:51], v44, s[88:91], 0 offen sc1
	v_cvt_pk_bf16_f32 v56, v56, v57
	v_cvt_pk_bf16_f32 v57, v58, v59
	v_cvt_pk_bf16_f32 v58, v60, v61
	v_cvt_pk_bf16_f32 v59, v62, v63
	buffer_store_dwordx4 v[56:59], v44, s[88:91], 0 offen offset:1024 sc1
	s_waitcnt vmcnt(26)
	v_mul_f32_e32 v45, v65, v65
	v_mul_f32_e32 v46, v67, v67
	v_fmac_f32_e32 v45, v64, v64
	v_fmac_f32_e32 v46, v66, v66
	v_add_f32_e32 v181, v45, v46
	v_mul_f32_e32 v45, v69, v69
	v_mul_f32_e32 v46, v71, v71
	v_fmac_f32_e32 v45, v68, v68
	v_fmac_f32_e32 v46, v70, v70
	v_add_f32_e32 v47, v45, v46
	v_add_f32_e32 v181, v181, v47
	v_mul_f32_e32 v45, v73, v73
	v_mul_f32_e32 v46, v75, v75
	v_fmac_f32_e32 v45, v72, v72
	v_fmac_f32_e32 v46, v74, v74
	v_add_f32_e32 v47, v45, v46
	v_add_f32_e32 v181, v181, v47
	v_mul_f32_e32 v45, v77, v77
	v_mul_f32_e32 v46, v79, v79
	v_fmac_f32_e32 v45, v76, v76
	v_fmac_f32_e32 v46, v78, v78
	v_add_f32_e32 v47, v45, v46
	v_add_f32_e32 v181, v181, v47
	s_lshl_b32 s14, s3, 11
	s_add_i32 s3, s3, s80
	v_add_u32_e32 v44, s14, v43
	v_cvt_pk_bf16_f32 v64, v64, v65
	v_cvt_pk_bf16_f32 v65, v66, v67
	v_cvt_pk_bf16_f32 v66, v68, v69
	v_cvt_pk_bf16_f32 v67, v70, v71
	buffer_store_dwordx4 v[64:67], v44, s[88:91], 0 offen sc1
	v_cvt_pk_bf16_f32 v72, v72, v73
	v_cvt_pk_bf16_f32 v73, v74, v75
	v_cvt_pk_bf16_f32 v74, v76, v77
	v_cvt_pk_bf16_f32 v75, v78, v79
	buffer_store_dwordx4 v[72:75], v44, s[88:91], 0 offen offset:1024 sc1
	s_waitcnt vmcnt(24)
; __device__ __forceinline__ unsigned pk2(float lo, float hi) { return pg8::cvt_pk_bf16(lo, hi); }
; __device__ __forceinline__ void wt_store16(const WsRef& w, const void* p, u32x4 v) { __builtin_amdgcn_raw_buffer_store_b128(v, w.r, (unsigned)((const unsigned char*)p - w.base), 0, 16); }
; __global__ void __launch_bounds__(512, 2) fwd_mega(Args a) {
;     ...
;             const f32x4* xr0 = (const f32x4*)(x + (size_t)m * D) + 2 * lane; const f32x4* xr1 = (const f32x4*)(x + (size_t)m2 * D) + 2 * lane;
;             f32x4 v0[4], v1[4]; float s0 = 0.f, s1 = 0.f;
; #pragma unroll
;             for (int j = 0; j < 2; ++j) { v0[2 * j] = xr0[128 * j]; v0[2 * j + 1] = xr0[128 * j + 1]; v1[2 * j] = xr1[128 * j]; v1[2 * j + 1] = xr1[128 * j + 1]; }
; #pragma unroll
;             for (int j = 0; j < 4; ++j) { s0 += (v0[j].x * v0[j].x + v0[j].y * v0[j].y) + (v0[j].z * v0[j].z + v0[j].w * v0[j].w); s1 += (v1[j].x * v1[j].x + v1[j].y * v1[j].y) + (v1[j].z * v1[j].z + v1[j].w * v1[j].w); }
; #pragma unroll
;             for (int o = 1; o < 64; o <<= 1) { s0 += __shfl_xor(s0, o); s1 += __shfl_xor(s1, o); }
;             if (lane == 0) { RSQX[m] = s0; RSQX[m2] = s1; }
;             bf16* o0 = H + (size_t)m * D + 8 * lane; bf16* o1 = H + (size_t)m2 * D + 8 * lane;
; #pragma unroll
;             for (int j = 0; j < 2; ++j) { const f32x4 a0 = v0[2 * j], b0 = v0[2 * j + 1], a1 = v1[2 * j], b1 = v1[2 * j + 1];
;                 u32x4 p0, p1; p0.x = pk2(a0.x, a0.y); p0.y = pk2(a0.z, a0.w); p0.z = pk2(b0.x, b0.y); p0.w = pk2(b0.z, b0.w); p1.x = pk2(a1.x, a1.y); p1.y = pk2(a1.z, a1.w); p1.z = pk2(b1.x, b1.y); p1.w = pk2(b1.z, b1.w);
;                 wt_store16(wsr, o0 + 512 * j, p0); if (m2 != m) wt_store16(wsr, o1 + 512 * j, p1); }
	v_mul_f32_e32 v45, v81, v81
	v_mul_f32_e32 v46, v83, v83
	v_fmac_f32_e32 v45, v80, v80
	v_fmac_f32_e32 v46, v82, v82
	v_add_f32_e32 v182, v45, v46
	v_mul_f32_e32 v45, v85, v85
	v_mul_f32_e32 v46, v87, v87
	v_fmac_f32_e32 v45, v84, v84
	v_fmac_f32_e32 v46, v86, v86
	v_add_f32_e32 v47, v45, v46
	v_add_f32_e32 v182, v182, v47
	v_mul_f32_e32 v45, v89, v89
	v_mul_f32_e32 v46, v91, v91
	v_fmac_f32_e32 v45, v88, v88
	v_fmac_f32_e32 v46, v90, v90
	v_add_f32_e32 v47, v45, v46
	v_add_f32_e32 v182, v182, v47
	v_mul_f32_e32 v45, v93, v93
	v_mul_f32_e32 v46, v95, v95
	v_fmac_f32_e32 v45, v92, v92
	v_fmac_f32_e32 v46, v94, v94
	v_add_f32_e32 v47, v45, v46
	v_add_f32_e32 v182, v182, v47
	s_lshl_b32 s14, s3, 11
	s_add_i32 s3, s3, s80
	v_add_u32_e32 v44, s14, v43
	v_cvt_pk_bf16_f32 v80, v80, v81
	v_cvt_pk_bf16_f32 v81, v82, v83
	v_cvt_pk_bf16_f32 v82, v84, v85
	v_cvt_pk_bf16_f32 v83, v86, v87
	buffer_store_dwordx4 v[80:83], v44, s[88:91], 0 offen sc1
	v_cvt_pk_bf16_f32 v88, v88, v89
	v_cvt_pk_bf16_f32 v89, v90, v91
	v_cvt_pk_bf16_f32 v90, v92, v93
	v_cvt_pk_bf16_f32 v91, v94, v95
	buffer_store_dwordx4 v[88:91], v44, s[88:91], 0 offen offset:1024 sc1
	s_waitcnt vmcnt(22)
	v_mul_f32_e32 v45, v97, v97
	v_mul_f32_e32 v46, v99, v99
	v_fmac_f32_e32 v45, v96, v96
	v_fmac_f32_e32 v46, v98, v98
	v_add_f32_e32 v183, v45, v46
	v_mul_f32_e32 v45, v101, v101
	v_mul_f32_e32 v46, v103, v103
	v_fmac_f32_e32 v45, v100, v100
	v_fmac_f32_e32 v46, v102, v102
	v_add_f32_e32 v47, v45, v46
	v_add_f32_e32 v183, v183, v47
	v_mul_f32_e32 v45, v105, v105
	v_mul_f32_e32 v46, v107, v107
	v_fmac_f32_e32 v45, v104, v104
	v_fmac_f32_e32 v46, v106, v106
	v_add_f32_e32 v47, v45, v46
	v_add_f32_e32 v183, v183, v47
	v_mul_f32_e32 v45, v109, v109
	v_mul_f32_e32 v46, v111, v111
	v_fmac_f32_e32 v45, v108, v108
	v_fmac_f32_e32 v46, v110, v110
	v_add_f32_e32 v47, v45, v46
	v_add_f32_e32 v183, v183, v47
	s_lshl_b32 s14, s3, 11
	s_add_i32 s3, s3, s80
	v_add_u32_e32 v44, s14, v43
	v_cvt_pk_bf16_f32 v96, v96, v97
	v_cvt_pk_bf16_f32 v97, v98, v99
	v_cvt_pk_bf16_f32 v98, v100, v101
	v_cvt_pk_bf16_f32 v99, v102, v103
	buffer_store_dwordx4 v[96:99], v44, s[88:91], 0 offen sc1
	v_cvt_pk_bf16_f32 v104, v104, v105
	v_cvt_pk_bf16_f32 v105, v106, v107
	v_cvt_pk_bf16_f32 v106, v108, v109
	v_cvt_pk_bf16_f32 v107, v110, v111
	buffer_store_dwordx4 v[104:107], v44, s[88:91], 0 offen offset:1024 sc1
	s_waitcnt vmcnt(20)
	v_mul_f32_e32 v45, v113, v113
	v_mul_f32_e32 v46, v115, v115
	v_fmac_f32_e32 v45, v112, v112
	v_fmac_f32_e32 v46, v114, v114
	v_add_f32_e32 v184, v45, v46
	v_mul_f32_e32 v45, v117, v117
	v_mul_f32_e32 v46, v119, v119
	v_fmac_f32_e32 v45, v116, v116
	v_fmac_f32_e32 v46, v118, v118
	v_add_f32_e32 v47, v45, v46
	v_add_f32_e32 v184, v184, v47
	v_mul_f32_e32 v45, v121, v121
	v_mul_f32_e32 v46, v123, v123
	v_fmac_f32_e32 v45, v120, v120
	v_fmac_f32_e32 v46, v122, v122
	v_add_f32_e32 v47, v45, v46
	v_add_f32_e32 v184, v184, v47
	v_mul_f32_e32 v45, v125, v125
	v_mul_f32_e32 v46, v127, v127
	v_fmac_f32_e32 v45, v124, v124
	v_fmac_f32_e32 v46, v126, v126
	v_add_f32_e32 v47, v45, v46
	v_add_f32_e32 v184, v184, v47
	s_lshl_b32 s14, s3, 11
	s_add_i32 s3, s3, s80
	v_add_u32_e32 v44, s14, v43
	v_cvt_pk_bf16_f32 v112, v112, v113
	v_cvt_pk_bf16_f32 v113, v114, v115
	v_cvt_pk_bf16_f32 v114, v116, v117
	v_cvt_pk_bf16_f32 v115, v118, v119
	buffer_store_dwordx4 v[112:115], v44, s[88:91], 0 offen sc1
	v_cvt_pk_bf16_f32 v120, v120, v121
	v_cvt_pk_bf16_f32 v121, v122, v123
	v_cvt_pk_bf16_f32 v122, v124, v125
	v_cvt_pk_bf16_f32 v123, v126, v127
	buffer_store_dwordx4 v[120:123], v44, s[88:91], 0 offen offset:1024 sc1
	s_waitcnt vmcnt(18)
	v_mul_f32_e32 v45, v131, v131
	v_mul_f32_e32 v46, v133, v133
	v_fmac_f32_e32 v45, v130, v130
	v_fmac_f32_e32 v46, v132, v132
	v_add_f32_e32 v185, v45, v46
	v_mul_f32_e32 v45, v135, v135
	v_mul_f32_e32 v46, v137, v137
	v_fmac_f32_e32 v45, v134, v134
	v_fmac_f32_e32 v46, v136, v136
	v_add_f32_e32 v47, v45, v46
	v_add_f32_e32 v185, v185, v47
	v_mul_f32_e32 v45, v139, v139
	v_mul_f32_e32 v46, v141, v141
	v_fmac_f32_e32 v45, v138, v138
	v_fmac_f32_e32 v46, v140, v140
	v_add_f32_e32 v47, v45, v46
	v_add_f32_e32 v185, v185, v47
	v_mul_f32_e32 v45, v143, v143
	v_mul_f32_e32 v46, v145, v145
	v_fmac_f32_e32 v45, v142, v142
	v_fmac_f32_e32 v46, v144, v144
	v_add_f32_e32 v47, v45, v46
	v_add_f32_e32 v185, v185, v47
	s_lshl_b32 s14, s3, 11
	s_add_i32 s3, s3, s80
	v_add_u32_e32 v44, s14, v43
	v_cvt_pk_bf16_f32 v130, v130, v131
	v_cvt_pk_bf16_f32 v131, v132, v133
	v_cvt_pk_bf16_f32 v132, v134, v135
	v_cvt_pk_bf16_f32 v133, v136, v137
	buffer_store_dwordx4 v[130:133], v44, s[88:91], 0 offen sc1
	v_cvt_pk_bf16_f32 v138, v138, v139
	v_cvt_pk_bf16_f32 v139, v140, v141
	v_cvt_pk_bf16_f32 v140, v142, v143
	v_cvt_pk_bf16_f32 v141, v144, v145
	buffer_store_dwordx4 v[138:141], v44, s[88:91], 0 offen offset:1024 sc1
	s_waitcnt vmcnt(16)
	v_mul_f32_e32 v45, v147, v147
	v_mul_f32_e32 v46, v149, v149
	v_fmac_f32_e32 v45, v146, v146
	v_fmac_f32_e32 v46, v148, v148
	v_add_f32_e32 v186, v45, v46
	v_mul_f32_e32 v45, v151, v151
	v_mul_f32_e32 v46, v153, v153
	v_fmac_f32_e32 v45, v150, v150
	v_fmac_f32_e32 v46, v152, v152
	v_add_f32_e32 v47, v45, v46
	v_add_f32_e32 v186, v186, v47
	v_mul_f32_e32 v45, v155, v155
	v_mul_f32_e32 v46, v157, v157
	v_fmac_f32_e32 v45, v154, v154
	v_fmac_f32_e32 v46, v156, v156
	v_add_f32_e32 v47, v45, v46
	v_add_f32_e32 v186, v186, v47
	v_mul_f32_e32 v45, v159, v159
	v_mul_f32_e32 v46, v161, v161
	v_fmac_f32_e32 v45, v158, v158
	v_fmac_f32_e32 v46, v160, v160
	v_add_f32_e32 v47, v45, v46
	v_add_f32_e32 v186, v186, v47
	s_lshl_b32 s14, s3, 11
	s_add_i32 s3, s3, s80
	v_add_u32_e32 v44, s14, v43
	v_cvt_pk_bf16_f32 v146, v146, v147
	v_cvt_pk_bf16_f32 v147, v148, v149
	v_cvt_pk_bf16_f32 v148, v150, v151
	v_cvt_pk_bf16_f32 v149, v152, v153
	buffer_store_dwordx4 v[146:149], v44, s[88:91], 0 offen sc1
	v_cvt_pk_bf16_f32 v154, v154, v155
	v_cvt_pk_bf16_f32 v155, v156, v157
	v_cvt_pk_bf16_f32 v156, v158, v159
	v_cvt_pk_bf16_f32 v157, v160, v161
	buffer_store_dwordx4 v[154:157], v44, s[88:91], 0 offen offset:1024 sc1
	s_waitcnt vmcnt(14)
; __device__ __forceinline__ unsigned pk2(float lo, float hi) { return pg8::cvt_pk_bf16(lo, hi); }
; __device__ __forceinline__ void wt_store16(const WsRef& w, const void* p, u32x4 v) { __builtin_amdgcn_raw_buffer_store_b128(v, w.r, (unsigned)((const unsigned char*)p - w.base), 0, 16); }
; __global__ void __launch_bounds__(512, 2) fwd_mega(Args a) {
;     ...
;             for (int j = 0; j < 4; ++j) { s0 += (v0[j].x * v0[j].x + v0[j].y * v0[j].y) + (v0[j].z * v0[j].z + v0[j].w * v0[j].w); s1 += (v1[j].x * v1[j].x + v1[j].y * v1[j].y) + (v1[j].z * v1[j].z + v1[j].w * v1[j].w); }
; #pragma unroll
;             for (int o = 1; o < 64; o <<= 1) { s0 += __shfl_xor(s0, o); s1 += __shfl_xor(s1, o); }
;             if (lane == 0) { RSQX[m] = s0; RSQX[m2] = s1; }
;             bf16* o0 = H + (size_t)m * D + 8 * lane; bf16* o1 = H + (size_t)m2 * D + 8 * lane;
; #pragma unroll
;             for (int j = 0; j < 2; ++j) { const f32x4 a0 = v0[2 * j], b0 = v0[2 * j + 1], a1 = v1[2 * j], b1 = v1[2 * j + 1];
;                 u32x4 p0, p1; p0.x = pk2(a0.x, a0.y); p0.y = pk2(a0.z, a0.w); p0.z = pk2(b0.x, b0.y); p0.w = pk2(b0.z, b0.w); p1.x = pk2(a1.x, a1.y); p1.y = pk2(a1.z, a1.w); p1.z = pk2(b1.x, b1.y); p1.w = pk2(b1.z, b1.w);
;                 wt_store16(wsr, o0 + 512 * j, p0); if (m2 != m) wt_store16(wsr, o1 + 512 * j, p1); }
	v_mul_f32_e32 v45, v163, v163
	v_mul_f32_e32 v46, v165, v165
	v_fmac_f32_e32 v45, v162, v162
	v_fmac_f32_e32 v46, v164, v164
	v_add_f32_e32 v187, v45, v46
	v_mul_f32_e32 v45, v167, v167
	v_mul_f32_e32 v46, v169, v169
	v_fmac_f32_e32 v45, v166, v166
	v_fmac_f32_e32 v46, v168, v168
	v_add_f32_e32 v47, v45, v46
	v_add_f32_e32 v187, v187, v47
	v_mul_f32_e32 v45, v171, v171
	v_mul_f32_e32 v46, v173, v173
	v_fmac_f32_e32 v45, v170, v170
	v_fmac_f32_e32 v46, v172, v172
	v_add_f32_e32 v47, v45, v46
	v_add_f32_e32 v187, v187, v47
	v_mul_f32_e32 v45, v175, v175
	v_mul_f32_e32 v46, v177, v177
	v_fmac_f32_e32 v45, v174, v174
	v_fmac_f32_e32 v46, v176, v176
	v_add_f32_e32 v47, v45, v46
	v_add_f32_e32 v187, v187, v47
	s_lshl_b32 s14, s3, 11
	s_add_i32 s3, s3, s80
	v_add_u32_e32 v44, s14, v43
	v_cvt_pk_bf16_f32 v162, v162, v163
	v_cvt_pk_bf16_f32 v163, v164, v165
	v_cvt_pk_bf16_f32 v164, v166, v167
	v_cvt_pk_bf16_f32 v165, v168, v169
	buffer_store_dwordx4 v[162:165], v44, s[88:91], 0 offen sc1
	v_cvt_pk_bf16_f32 v170, v170, v171
	v_cvt_pk_bf16_f32 v171, v172, v173
	v_cvt_pk_bf16_f32 v172, v174, v175
	v_cvt_pk_bf16_f32 v173, v176, v177
	buffer_store_dwordx4 v[170:173], v44, s[88:91], 0 offen offset:1024 sc1
	ds_bpermute_b32 v188, v32, v180
	ds_bpermute_b32 v189, v32, v181
	ds_bpermute_b32 v190, v32, v182
	ds_bpermute_b32 v191, v32, v183
	ds_bpermute_b32 v192, v32, v184
	ds_bpermute_b32 v193, v32, v185
	ds_bpermute_b32 v194, v32, v186
	ds_bpermute_b32 v195, v32, v187
	s_waitcnt lgkmcnt(0)
	v_add_f32_e32 v180, v180, v188
	v_add_f32_e32 v181, v181, v189
	v_add_f32_e32 v182, v182, v190
	v_add_f32_e32 v183, v183, v191
	v_add_f32_e32 v184, v184, v192
	v_add_f32_e32 v185, v185, v193
	v_add_f32_e32 v186, v186, v194
	v_add_f32_e32 v187, v187, v195
	ds_bpermute_b32 v188, v38, v180
	ds_bpermute_b32 v189, v38, v181
	ds_bpermute_b32 v190, v38, v182
	ds_bpermute_b32 v191, v38, v183
	ds_bpermute_b32 v192, v38, v184
	ds_bpermute_b32 v193, v38, v185
	ds_bpermute_b32 v194, v38, v186
	ds_bpermute_b32 v195, v38, v187
	s_waitcnt lgkmcnt(0)
	v_add_f32_e32 v180, v180, v188
	v_add_f32_e32 v181, v181, v189
	v_add_f32_e32 v182, v182, v190
	v_add_f32_e32 v183, v183, v191
	v_add_f32_e32 v184, v184, v192
	v_add_f32_e32 v185, v185, v193
	v_add_f32_e32 v186, v186, v194
	v_add_f32_e32 v187, v187, v195
	ds_bpermute_b32 v188, v39, v180
	ds_bpermute_b32 v189, v39, v181
	ds_bpermute_b32 v190, v39, v182
	ds_bpermute_b32 v191, v39, v183
	ds_bpermute_b32 v192, v39, v184
	ds_bpermute_b32 v193, v39, v185
	ds_bpermute_b32 v194, v39, v186
	ds_bpermute_b32 v195, v39, v187
	s_waitcnt lgkmcnt(0)
	v_add_f32_e32 v180, v180, v188
	v_add_f32_e32 v181, v181, v189
	v_add_f32_e32 v182, v182, v190
	v_add_f32_e32 v183, v183, v191
	v_add_f32_e32 v184, v184, v192
	v_add_f32_e32 v185, v185, v193
	v_add_f32_e32 v186, v186, v194
	v_add_f32_e32 v187, v187, v195
	ds_bpermute_b32 v188, v40, v180
	ds_bpermute_b32 v189, v40, v181
	ds_bpermute_b32 v190, v40, v182
	ds_bpermute_b32 v191, v40, v183
	ds_bpermute_b32 v192, v40, v184
	ds_bpermute_b32 v193, v40, v185
	ds_bpermute_b32 v194, v40, v186
	ds_bpermute_b32 v195, v40, v187
	s_waitcnt lgkmcnt(0)
	v_add_f32_e32 v180, v180, v188
	v_add_f32_e32 v181, v181, v189
	v_add_f32_e32 v182, v182, v190
	v_add_f32_e32 v183, v183, v191
	v_add_f32_e32 v184, v184, v192
	v_add_f32_e32 v185, v185, v193
	v_add_f32_e32 v186, v186, v194
	v_add_f32_e32 v187, v187, v195
	ds_bpermute_b32 v188, v41, v180
	ds_bpermute_b32 v189, v41, v181
	ds_bpermute_b32 v190, v41, v182
	ds_bpermute_b32 v191, v41, v183
	ds_bpermute_b32 v192, v41, v184
	ds_bpermute_b32 v193, v41, v185
	ds_bpermute_b32 v194, v41, v186
	ds_bpermute_b32 v195, v41, v187
	s_waitcnt lgkmcnt(0)
	v_add_f32_e32 v180, v180, v188
	v_add_f32_e32 v181, v181, v189
	v_add_f32_e32 v182, v182, v190
	v_add_f32_e32 v183, v183, v191
	v_add_f32_e32 v184, v184, v192
	v_add_f32_e32 v185, v185, v193
	v_add_f32_e32 v186, v186, v194
	v_add_f32_e32 v187, v187, v195
	ds_bpermute_b32 v188, v42, v180
	ds_bpermute_b32 v189, v42, v181
	ds_bpermute_b32 v190, v42, v182
	ds_bpermute_b32 v191, v42, v183
	ds_bpermute_b32 v192, v42, v184
	ds_bpermute_b32 v193, v42, v185
	ds_bpermute_b32 v194, v42, v186
	ds_bpermute_b32 v195, v42, v187
	s_waitcnt lgkmcnt(0)
	v_add_f32_e32 v180, v180, v188
	v_add_f32_e32 v181, v181, v189
	v_add_f32_e32 v182, v182, v190
	v_add_f32_e32 v183, v183, v191
	v_add_f32_e32 v184, v184, v192
	v_add_f32_e32 v185, v185, v193
	v_add_f32_e32 v186, v186, v194
	v_add_f32_e32 v187, v187, v195
	s_mov_b32 s3, s6
	s_and_saveexec_b64 s[14:15], s[0:1]
	s_lshl_b32 s16, s3, 2
	s_add_i32 s3, s3, s80
	s_add_u32 s16, s28, s16
	s_addc_u32 s17, s29, 0
	global_store_dword v33, v180, s[16:17]
	s_lshl_b32 s16, s3, 2
	s_add_i32 s3, s3, s80
	s_add_u32 s16, s28, s16
	s_addc_u32 s17, s29, 0
	global_store_dword v33, v181, s[16:17]
	s_lshl_b32 s16, s3, 2
	s_add_i32 s3, s3, s80
	s_add_u32 s16, s28, s16
	s_addc_u32 s17, s29, 0
	global_store_dword v33, v182, s[16:17]
	s_lshl_b32 s16, s3, 2
	s_add_i32 s3, s3, s80
	s_add_u32 s16, s28, s16
	s_addc_u32 s17, s29, 0
	global_store_dword v33, v183, s[16:17]
	s_lshl_b32 s16, s3, 2
	s_add_i32 s3, s3, s80
	s_add_u32 s16, s28, s16
	s_addc_u32 s17, s29, 0
	global_store_dword v33, v184, s[16:17]
	s_lshl_b32 s16, s3, 2
	s_add_i32 s3, s3, s80
	s_add_u32 s16, s28, s16
	s_addc_u32 s17, s29, 0
	global_store_dword v33, v185, s[16:17]
	s_lshl_b32 s16, s3, 2
	s_add_i32 s3, s3, s80
	s_add_u32 s16, s28, s16
	s_addc_u32 s17, s29, 0
	global_store_dword v33, v186, s[16:17]
	s_lshl_b32 s16, s3, 2
	s_add_i32 s3, s3, s80
	s_add_u32 s16, s28, s16
	s_addc_u32 s17, s29, 0
	global_store_dword v33, v187, s[16:17]
	s_or_b64 exec, exec, s[14:15]
	s_mov_b32 s9, 0
	s_branch .LBB0_66

; #define LAS __attribute__((address_space(3)))
; __device__ __forceinline__ float log_sigmoid(float x) { return -log1pf(expf(-x)); }
; __device__ __forceinline__ void ret_unit(LAS unsigned char* lds, int u, const bf16* PROJ, const int* pos, const float* dec_f, const float* dec_b, const bf16* ST,
;                                          const float* gn_w, const float* gn_b, bf16* MIX, int tid, const WsRef& wsr) {
;     const int lane = tid & 63, wave = tid >> 6, fr = lane & 15, fq = lane >> 4;
;     const int bh = u >> 6, c = u & 63, b = bh >> 2, h = bh & 3;
;     const size_t row0 = (size_t)b * SEQ + (size_t)c * 128;
;     LAS bf16* Qs = (LAS bf16*)lds; LAS bf16* Ks = (LAS bf16*)(lds + TILE_B); LAS bf16* VT = (LAS bf16*)(lds + 2 * TILE_B);
;     const float lgf2 = log_sigmoid(dec_f[h]) * LOG2E, lgb2 = log_sigmoid(dec_b[h]) * LOG2E;
.LBB0_438:
	s_ashr_i32 s0, s73, 6
	s_and_b32 s80, s0, 3
	s_lshl_b32 s1, s80, 2
	v_mov_b32_e32 v16, s1
	global_load_dword v0, v16, s[18:19]
	s_mov_b32 s1, 0x42ce8ed0
	s_mov_b32 s83, 0xc2b17218
	s_mov_b32 s11, 0x3f2aaaab
	s_mov_b32 s88, 0x7f800000
	s_mov_b32 s8, 0x33800000
	s_and_b32 s82, s73, 63
	s_ashr_i32 s4, s73, 8
	s_ashr_i32 s5, s4, 31
	s_lshl_b32 s81, s82, 7
	s_waitcnt vmcnt(0)
	v_mul_f32_e32 v1, 0xbfb8aa3b, v0
	v_fma_f32 v2, v0, s41, -v1
	v_rndne_f32_e32 v3, v1
	v_fmac_f32_e32 v2, 0xb2a5705f, v0
	v_sub_f32_e32 v1, v1, v3
	v_add_f32_e32 v1, v1, v2
	v_exp_f32_e32 v1, v1
	v_cvt_i32_f32_e32 v2, v3
	v_cmp_nlt_f32_e64 s[68:69], s1, v0
	v_ldexp_f32 v1, v1, v2
	s_nop 0
	v_cndmask_b32_e64 v1, 0, v1, s[68:69]
	v_cmp_ngt_f32_e64 s[68:69], s83, v0
	s_nop 1
	v_cndmask_b32_e64 v17, v228, v1, s[68:69]
	v_add_f32_e32 v2, 1.0, v17
	v_add_f32_e32 v0, -1.0, v2
	v_sub_f32_e32 v1, v0, v2
	v_add_f32_e32 v1, 1.0, v1
	v_sub_f32_e32 v0, v17, v0
	v_add_f32_e32 v3, v0, v1
	v_frexp_mant_f32_e32 v0, v2
	v_cmp_gt_f32_e64 s[68:69], s11, v0
	v_cvt_f64_f32_e32 v[0:1], v2
	v_frexp_exp_i32_f64_e32 v0, v[0:1]
	v_subbrev_co_u32_e64 v8, s[68:69], 0, v0, s[68:69]
	v_sub_u32_e32 v0, 0, v8
	v_ldexp_f32 v1, v2, v0
	v_add_f32_e32 v2, -1.0, v1
	v_add_f32_e32 v4, 1.0, v1
	v_ldexp_f32 v0, v3, v0
	v_add_f32_e32 v3, 1.0, v2
	v_add_f32_e32 v5, -1.0, v4
	v_sub_f32_e32 v3, v1, v3
	v_sub_f32_e32 v1, v1, v5
	v_add_f32_e32 v3, v0, v3
	v_add_f32_e32 v0, v0, v1
	v_add_f32_e32 v9, v4, v0
	v_rcp_f32_e32 v11, v9
	v_sub_f32_e32 v1, v4, v9
	v_add_f32_e32 v10, v0, v1
	v_add_f32_e32 v1, v2, v3
	v_mul_f32_e32 v13, v1, v11
	v_sub_f32_e32 v0, v2, v1
	v_mul_f32_e32 v2, v9, v13
	v_fma_f32 v4, v13, v9, -v2
	v_fmac_f32_e32 v4, v13, v10
	v_add_f32_e32 v12, v3, v0
	v_add_f32_e32 v0, v2, v4
	v_sub_f32_e32 v3, v1, v0
	v_pk_add_f32 v[6:7], v[0:1], v[2:3] neg_lo:[0,1] neg_hi:[0,1]
	v_mov_b32_e32 v5, v0
	v_pk_add_f32 v[0:1], v[6:7], v[4:5] neg_lo:[0,1] neg_hi:[0,1]
	v_cmp_neq_f32_e64 s[68:69], s88, v17
	v_add_f32_e32 v1, v12, v1
	v_add_f32_e32 v0, v0, v1
	v_add_f32_e32 v1, v3, v0
	v_mul_f32_e32 v12, v11, v1
	v_mul_f32_e32 v2, v9, v12
	v_fma_f32 v4, v12, v9, -v2
	v_fmac_f32_e32 v4, v12, v10
	v_sub_f32_e32 v3, v3, v1
	v_add_f32_e32 v9, v0, v3
	v_add_f32_e32 v0, v2, v4
	v_sub_f32_e32 v3, v1, v0
	v_pk_add_f32 v[6:7], v[0:1], v[2:3] neg_lo:[0,1] neg_hi:[0,1]
	v_mov_b32_e32 v5, v0
	v_pk_add_f32 v[0:1], v[6:7], v[4:5] neg_lo:[0,1] neg_hi:[0,1]
	s_nop 0
	v_add_f32_e32 v1, v9, v1
	v_add_f32_e32 v0, v0, v1
	v_add_f32_e32 v1, v13, v12
	v_add_f32_e32 v0, v3, v0
	v_sub_f32_e32 v2, v1, v13
	v_mul_f32_e32 v0, v11, v0
	v_sub_f32_e32 v2, v12, v2
	v_add_f32_e32 v2, v2, v0
	v_add_f32_e32 v4, v1, v2
	v_mul_f32_e32 v5, v4, v4
	v_fmamk_f32 v0, v5, 0x3e9b6dac, v223
	v_fmaak_f32 v105, v5, v0, 0x3f2aaada
	v_cvt_f32_i32_e32 v0, v8
	v_sub_f32_e32 v1, v4, v1
	v_sub_f32_e32 v1, v2, v1
	v_ldexp_f32 v6, v1, 1
	v_mul_f32_e32 v1, v4, v5
	v_ldexp_f32 v3, v4, 1
	v_pk_mul_f32 v[4:5], v[0:1], v[104:105]
	s_nop 0
	v_fma_f32 v2, v0, s33, -v4
	v_fmac_f32_e32 v2, 0xb102e308, v0
	v_pk_add_f32 v[0:1], v[4:5], v[2:3]
	s_nop 0
	v_sub_f32_e32 v3, v1, v3
	v_sub_f32_e32 v3, v5, v3
	v_add_f32_e32 v7, v6, v3
	v_mov_b32_e32 v6, v4
	v_pk_add_f32 v[4:5], v[0:1], v[4:5] neg_lo:[0,1] neg_hi:[0,1]
	v_pk_add_f32 v[8:9], v[0:1], v[6:7]
	v_mov_b32_e32 v3, v0
	v_mov_b32_e32 v5, v9
	v_pk_add_f32 v[10:11], v[2:3], v[4:5] neg_lo:[0,1] neg_hi:[0,1]
	v_pk_add_f32 v[2:3], v[2:3], v[4:5]
	v_mov_b32_e32 v14, v1
	v_pk_add_f32 v[4:5], v[2:3], v[0:1] op_sel:[1,0] op_sel_hi:[0,1] neg_lo:[0,1] neg_hi:[0,1]
	v_pk_add_f32 v[12:13], v[8:9], v[4:5] op_sel_hi:[1,0] neg_lo:[0,1] neg_hi:[0,1]
	v_mov_b32_e32 v8, v9
	v_mov_b32_e32 v9, v3
	v_mov_b32_e32 v15, v4
	v_pk_add_f32 v[4:5], v[8:9], v[14:15] neg_lo:[0,1] neg_hi:[0,1]
	v_mov_b32_e32 v6, v7
	v_mov_b32_e32 v7, v0
	v_pk_add_f32 v[0:1], v[6:7], v[4:5] neg_lo:[0,1] neg_hi:[0,1]
	v_mov_b32_e32 v12, v10
	v_pk_add_f32 v[4:5], v[12:13], v[0:1]
	v_mov_b32_e32 v11, v3
	v_pk_add_f32 v[6:7], v[4:5], v[4:5] op_sel:[0,1] op_sel_hi:[1,0]
	s_nop 0
	v_pk_add_f32 v[2:3], v[2:3], v[6:7] op_sel:[1,0] op_sel_hi:[0,1]
	v_mov_b32_e32 v5, v2
	v_pk_add_f32 v[8:9], v[4:5], v[10:11] neg_lo:[0,1] neg_hi:[0,1]
	v_mov_b32_e32 v1, v6
	v_sub_f32_e32 v3, v4, v8
	v_pk_add_f32 v[0:1], v[0:1], v[8:9] neg_lo:[0,1] neg_hi:[0,1]
	v_sub_f32_e32 v3, v10, v3
	v_add_f32_e32 v0, v0, v3
	v_add_f32_e32 v0, v0, v1
	global_load_dword v1, v16, s[20:21]
	v_add_f32_e32 v0, v2, v0
	v_cndmask_b32_e64 v0, v228, v0, s[68:69]
	v_cmp_lt_f32_e64 s[68:69], |v17|, s8
	s_waitcnt vmcnt(0)
; __device__ __forceinline__ u32x4 ws_load16(const WsRef& w, unsigned byte_off) { return __builtin_bit_cast(u32x4, __builtin_amdgcn_raw_buffer_load_b128(w.r, byte_off, 0, 0)); }
; __device__ __forceinline__ float log_sigmoid(float x) { return -log1pf(expf(-x)); }
; __device__ __forceinline__ void ret_unit(LAS unsigned char* lds, int u, const bf16* PROJ, const int* pos, const float* dec_f, const float* dec_b, const bf16* ST,
;                                          const float* gn_w, const float* gn_b, bf16* MIX, int tid, const WsRef& wsr) {
;     ...
;     const float lgf2 = log_sigmoid(dec_f[h]) * LOG2E, lgb2 = log_sigmoid(dec_b[h]) * LOG2E;
;     const u32x4* sfp = (const u32x4*)(ST + ((size_t)bh * 64 + c) * 16384); const u32x4* sbp = (const u32x4*)(ST + ((size_t)(8 + bh) * 64 + c) * 16384);
;     u32x4 sf[4], sb[4];
; #pragma unroll
;     for (int i = 0; i < 4; ++i) { sf[i] = sfp[tid + 512 * i]; sb[i] = sbp[tid + 512 * i]; }
;     u32x4 rq1[2], rq2[2], rk1[2], rk2[2], rv[4]; float rp[2];
; #pragma unroll
;     for (int ii = 0; ii < 2; ++ii) { const int it = tid + 512 * ii, dc = it & 7, j = it >> 3; const unsigned qo = (unsigned)WS_PROJ + (unsigned)(((unsigned)(row0 + j) * INC + h * 128 + dc * 8) * 2u);
;         rq1[ii] = ws_load16(wsr, qo); rq2[ii] = ws_load16(wsr, qo + 128u); rk1[ii] = ws_load16(wsr, qo + 1024u); rk2[ii] = ws_load16(wsr, qo + 1152u); rp[ii] = (float)pos[row0 + j]; }
	v_mul_f32_e32 v2, 0xbfb8aa3b, v1
	v_fma_f32 v3, v1, s41, -v2
	v_rndne_f32_e32 v4, v2
	v_fmac_f32_e32 v3, 0xb2a5705f, v1
	v_sub_f32_e32 v2, v2, v4
	v_add_f32_e32 v2, v2, v3
	v_exp_f32_e32 v2, v2
	v_cvt_i32_f32_e32 v3, v4
	v_cndmask_b32_e64 v0, v0, v17, s[68:69]
	v_cmp_nlt_f32_e64 s[68:69], s1, v1
	s_ashr_i32 s1, s0, 31
	v_ldexp_f32 v2, v2, v3
	v_cndmask_b32_e64 v2, 0, v2, s[68:69]
	v_cmp_ngt_f32_e64 s[68:69], s83, v1
	s_lshl_b64 s[0:1], s[0:1], 21
	s_add_u32 s0, s54, s0
	v_cndmask_b32_e64 v1, v228, v2, s[68:69]
	v_add_f32_e32 v4, 1.0, v1
	v_add_f32_e32 v2, -1.0, v4
	v_sub_f32_e32 v3, v2, v4
	v_add_f32_e32 v3, 1.0, v3
	v_sub_f32_e32 v2, v1, v2
	v_add_f32_e32 v5, v2, v3
	v_frexp_mant_f32_e32 v2, v4
	v_cmp_gt_f32_e64 s[68:69], s11, v2
	v_cvt_f64_f32_e32 v[2:3], v4
	v_frexp_exp_i32_f64_e32 v2, v[2:3]
	v_subbrev_co_u32_e64 v10, s[68:69], 0, v2, s[68:69]
	v_sub_u32_e32 v2, 0, v10
	v_ldexp_f32 v3, v4, v2
	v_add_f32_e32 v4, -1.0, v3
	v_add_f32_e32 v6, 1.0, v3
	v_ldexp_f32 v2, v5, v2
	v_add_f32_e32 v5, 1.0, v4
	v_add_f32_e32 v7, -1.0, v6
	v_sub_f32_e32 v5, v3, v5
	v_sub_f32_e32 v3, v3, v7
	v_add_f32_e32 v5, v2, v5
	v_add_f32_e32 v2, v2, v3
	v_add_f32_e32 v11, v6, v2
	v_rcp_f32_e32 v13, v11
	v_sub_f32_e32 v3, v6, v11
	v_add_f32_e32 v12, v2, v3
	v_add_f32_e32 v3, v4, v5
	v_mul_f32_e32 v15, v3, v13
	v_sub_f32_e32 v2, v4, v3
	v_mul_f32_e32 v4, v11, v15
	v_fma_f32 v6, v15, v11, -v4
	v_fmac_f32_e32 v6, v15, v12
	v_add_f32_e32 v14, v5, v2
	v_add_f32_e32 v2, v4, v6
	v_sub_f32_e32 v5, v3, v2
	v_pk_add_f32 v[8:9], v[2:3], v[4:5] neg_lo:[0,1] neg_hi:[0,1]
	v_mov_b32_e32 v7, v2
	v_pk_add_f32 v[2:3], v[8:9], v[6:7] neg_lo:[0,1] neg_hi:[0,1]
	v_cmp_neq_f32_e64 s[68:69], s88, v1
	v_add_f32_e32 v3, v14, v3
	v_add_f32_e32 v2, v2, v3
	v_add_f32_e32 v3, v5, v2
	v_mul_f32_e32 v14, v13, v3
	v_mul_f32_e32 v4, v11, v14
	v_fma_f32 v6, v14, v11, -v4
	v_fmac_f32_e32 v6, v14, v12
	v_sub_f32_e32 v5, v5, v3
	v_add_f32_e32 v11, v2, v5
	v_add_f32_e32 v2, v4, v6
	v_sub_f32_e32 v5, v3, v2
	v_pk_add_f32 v[8:9], v[2:3], v[4:5] neg_lo:[0,1] neg_hi:[0,1]
	v_mov_b32_e32 v7, v2
	v_pk_add_f32 v[2:3], v[8:9], v[6:7] neg_lo:[0,1] neg_hi:[0,1]
	s_addc_u32 s1, s55, s1
	v_add_f32_e32 v3, v11, v3
	v_add_f32_e32 v2, v2, v3
	v_add_f32_e32 v3, v15, v14
	v_add_f32_e32 v2, v5, v2
	v_sub_f32_e32 v4, v3, v15
	v_mul_f32_e32 v2, v13, v2
	v_sub_f32_e32 v4, v14, v4
	v_add_f32_e32 v4, v4, v2
	v_add_f32_e32 v6, v3, v4
	v_mul_f32_e32 v7, v6, v6
	v_fmamk_f32 v2, v7, 0x3e9b6dac, v223
	v_fmaak_f32 v105, v7, v2, 0x3f2aaada
	v_cvt_f32_i32_e32 v2, v10
	v_sub_f32_e32 v3, v6, v3
	v_sub_f32_e32 v3, v4, v3
	v_ldexp_f32 v8, v3, 1
	v_mul_f32_e32 v3, v6, v7
	v_ldexp_f32 v5, v6, 1
	v_pk_mul_f32 v[6:7], v[2:3], v[104:105]
	v_mul_f32_e32 v105, 0xbfb8aa3b, v0
	v_fma_f32 v4, v2, s33, -v6
	v_fmac_f32_e32 v4, 0xb102e308, v2
	v_pk_add_f32 v[2:3], v[6:7], v[4:5]
	s_mov_b32 s88, s84
	v_sub_f32_e32 v5, v3, v5
	v_sub_f32_e32 v5, v7, v5
	v_add_f32_e32 v9, v8, v5
	v_mov_b32_e32 v8, v6
	v_pk_add_f32 v[6:7], v[2:3], v[6:7] neg_lo:[0,1] neg_hi:[0,1]
	v_pk_add_f32 v[10:11], v[2:3], v[8:9]
	v_mov_b32_e32 v5, v2
	v_mov_b32_e32 v7, v11
	v_pk_add_f32 v[12:13], v[4:5], v[6:7] neg_lo:[0,1] neg_hi:[0,1]
	v_pk_add_f32 v[4:5], v[4:5], v[6:7]
	v_mov_b32_e32 v16, v3
	v_pk_add_f32 v[6:7], v[4:5], v[2:3] op_sel:[1,0] op_sel_hi:[0,1] neg_lo:[0,1] neg_hi:[0,1]
	v_pk_add_f32 v[14:15], v[10:11], v[6:7] op_sel_hi:[1,0] neg_lo:[0,1] neg_hi:[0,1]
	v_mov_b32_e32 v10, v11
	v_mov_b32_e32 v11, v5
	v_mov_b32_e32 v17, v6
	v_pk_add_f32 v[6:7], v[10:11], v[16:17] neg_lo:[0,1] neg_hi:[0,1]
	v_mov_b32_e32 v8, v9
	v_mov_b32_e32 v9, v2
	v_pk_add_f32 v[2:3], v[8:9], v[6:7] neg_lo:[0,1] neg_hi:[0,1]
	v_mov_b32_e32 v14, v12
	v_pk_add_f32 v[6:7], v[14:15], v[2:3]
	v_mov_b32_e32 v13, v5
	v_pk_add_f32 v[8:9], v[6:7], v[6:7] op_sel:[0,1] op_sel_hi:[1,0]
	s_nop 0
	v_pk_add_f32 v[4:5], v[4:5], v[8:9] op_sel:[1,0] op_sel_hi:[0,1]
	v_mov_b32_e32 v7, v4
	v_pk_add_f32 v[10:11], v[6:7], v[12:13] neg_lo:[0,1] neg_hi:[0,1]
	v_mov_b32_e32 v3, v8
	v_sub_f32_e32 v5, v6, v10
	v_pk_add_f32 v[2:3], v[2:3], v[10:11] neg_lo:[0,1] neg_hi:[0,1]
	v_sub_f32_e32 v5, v12, v5
	v_add_f32_e32 v2, v2, v5
	v_add_f32_e32 v2, v2, v3
	v_add_f32_e32 v2, v4, v2
	v_cndmask_b32_e64 v2, v228, v2, s[68:69]
	v_cmp_lt_f32_e64 s[68:69], |v1|, s8
	s_movk_i32 s8, 0x2000
	s_nop 0
	v_cndmask_b32_e64 v48, v2, v1, s[68:69]
	s_lshl_b32 s68, s82, 15
	s_add_u32 s0, s0, s68
	s_addc_u32 s1, s1, 0
	s_add_u32 s82, s0, 0x1000000
	v_lshl_add_u64 v[2:3], s[0:1], 0, v[96:97]
	s_addc_u32 s83, s1, 0
	v_add_co_u32_e64 v8, s[68:69], s8, v2
	v_lshl_add_u64 v[28:29], s[82:83], 0, v[96:97]
	s_nop 0
	v_addc_co_u32_e64 v9, s[68:69], 0, v3, s[68:69]
	v_add_co_u32_e64 v16, s[68:69], s8, v28
	global_load_dwordx4 v[4:7], v96, s[0:1]
	global_load_dwordx4 v[12:15], v96, s[82:83]
	v_addc_co_u32_e64 v17, s[68:69], 0, v29, s[68:69]
	global_load_dwordx4 v[8:11], v[8:9], off
	s_nop 0
	global_load_dwordx4 v[16:19], v[16:17], off
	s_nop 0
	global_load_dwordx4 v[24:27], v224, s[0:1]
	global_load_dwordx4 v[20:23], v224, s[82:83]
	s_movk_i32 s0, 0x6000
	v_add_co_u32_e64 v2, s[68:69], s0, v2
	s_lshl_b64 s[4:5], s[4:5], 13
	s_nop 0
	v_addc_co_u32_e64 v3, s[68:69], 0, v3, s[68:69]
	global_load_dwordx4 v[32:35], v[2:3], off
	v_add_co_u32_e64 v2, s[68:69], s0, v28
	s_or_b32 s4, s4, s81
	s_nop 0
	v_addc_co_u32_e64 v3, s[68:69], 0, v29, s[68:69]
	s_lshl_b32 s0, s80, 7
	v_or_b32_e32 v0, s4, v98
	global_load_dwordx4 v[36:39], v[2:3], off
	v_or_b32_e32 v2, s0, v106
	v_mul_lo_u32 v3, v0, s9
	v_mov_b32_e32 v1, s5
	v_or_b32_e32 v3, v3, v2
	v_lshl_add_u32 v3, v3, 1, v229
	v_lshl_add_u64 v[0:1], v[0:1], 2, s[12:13]
	buffer_load_dwordx4 v[50:53], v3, s[88:91], 0 offen
; __device__ __forceinline__ u32x4 ws_load16(const WsRef& w, unsigned byte_off) { return __builtin_bit_cast(u32x4, __builtin_amdgcn_raw_buffer_load_b128(w.r, byte_off, 0, 0)); }
; __device__ __forceinline__ float fexp2(float x) { return __builtin_amdgcn_exp2f(x); }
; __device__ __forceinline__ void ret_unit(LAS unsigned char* lds, int u, const bf16* PROJ, const int* pos, const float* dec_f, const float* dec_b, const bf16* ST,
;                                          const float* gn_w, const float* gn_b, bf16* MIX, int tid, const WsRef& wsr) {
;     ...
;     for (int ii = 0; ii < 2; ++ii) { const int it = tid + 512 * ii, dc = it & 7, j = it >> 3; const unsigned qo = (unsigned)WS_PROJ + (unsigned)(((unsigned)(row0 + j) * INC + h * 128 + dc * 8) * 2u);
;         rq1[ii] = ws_load16(wsr, qo); rq2[ii] = ws_load16(wsr, qo + 128u); rk1[ii] = ws_load16(wsr, qo + 1024u); rk2[ii] = ws_load16(wsr, qo + 1152u); rp[ii] = (float)pos[row0 + j]; }
; #pragma unroll
;     for (int ii = 0; ii < 2; ++ii) { const int it = tid + 512 * ii, dc = it & 7, j = it >> 3;
;         const u32x4 q1 = rq1[ii], q2 = rq2[ii], k1 = rk1[ii], k2 = rk2[ii];
;         const float p = rp[ii];
;         float sn[8], cs[8];
; #pragma unroll
;         for (int e = 0; e < 8; ++e) { const int i = dc * 8 + e; const float inv = fexp2(-(float)i * 0.20762050593046015f); fast_sincos(p * inv, sn[e], cs[e]); }
	buffer_load_dwordx4 v[54:57], v3, s[88:91], 0 offen offset:128
	buffer_load_dwordx4 v[58:61], v3, s[88:91], 0 offen offset:1024
	buffer_load_dwordx4 v[62:65], v3, s[88:91], 0 offen offset:1152
	v_lshl_add_u64 v[66:67], s[4:5], 0, v[100:101]
	global_load_dword v0, v[0:1], off
	v_mul_f32_e32 v230, 0xbfb8aa3b, v48
	v_cndmask_b32_e64 v89, v105, v230, s[30:31]
	v_cndmask_b32_e64 v94, v105, v230, s[56:57]
	v_cndmask_b32_e64 v95, v105, v230, s[58:59]
	v_mul_f32_e32 v89, v89, v137
	v_cndmask_b32_e64 v92, v105, v230, s[74:75]
	v_cndmask_b32_e64 v93, v105, v230, s[76:77]
	v_mul_f32_e32 v94, v94, v142
	v_mul_f32_e32 v95, v95, v143
	v_exp_f32_e32 v89, v89
	v_mul_f32_e32 v92, v92, v140
	v_mul_f32_e32 v93, v93, v141
	v_exp_f32_e32 v94, v94
	v_exp_f32_e32 v95, v95
	v_exp_f32_e32 v92, v92
	v_exp_f32_e32 v93, v93
	v_cndmask_b32_e64 v130, v105, v230, s[60:61]
	v_cndmask_b32_e64 v131, v105, v230, s[62:63]
	v_cndmask_b32_e64 v48, v105, v230, s[42:43]
	v_mul_f32_e32 v130, v130, v144
	v_mul_f32_e32 v131, v131, v145
	v_mul_f32_e32 v48, v48, v127
	v_exp_f32_e32 v130, v130
	v_exp_f32_e32 v131, v131
	v_exp_f32_e32 v48, v48
	v_cndmask_b32_e64 v90, v105, v230, s[34:35]
	v_cndmask_b32_e64 v91, v105, v230, s[38:39]
	v_mul_f32_e32 v90, v90, v138
	v_mul_f32_e32 v91, v91, v139
	v_exp_f32_e32 v90, v90
	v_exp_f32_e32 v91, v91
	v_cndmask_b32_e64 v238, v105, v230, s[94:95]
	v_mul_f32_e32 v238, v238, v154
	v_exp_f32_e32 v238, v238
	v_cndmask_b32_e64 v234, v105, v230, s[78:79]
	v_cndmask_b32_e64 v235, v105, v230, s[2:3]
	v_cndmask_b32_e64 v236, v105, v230, s[92:93]
	v_cndmask_b32_e32 v237, v105, v230, vcc
	v_mul_f32_e32 v234, v234, v150
	v_mul_f32_e32 v235, v235, v151
	v_mul_f32_e32 v236, v236, v152
	v_mul_f32_e32 v237, v237, v153
	v_exp_f32_e32 v234, v234
	v_exp_f32_e32 v235, v235
	v_exp_f32_e32 v236, v236
	v_exp_f32_e32 v237, v237
	v_cndmask_b32_e64 v132, v105, v230, s[64:65]
	v_cndmask_b32_e64 v133, v105, v230, s[14:15]
	v_cndmask_b32_e64 v232, v105, v230, s[16:17]
	v_cndmask_b32_e64 v233, v105, v230, s[24:25]
	v_mul_f32_e32 v132, v132, v146
	v_mul_f32_e32 v133, v133, v147
	v_mul_f32_e32 v232, v232, v148
	v_mul_f32_e32 v233, v233, v149
	v_exp_f32_e32 v132, v132
	v_exp_f32_e32 v133, v133
	v_exp_f32_e32 v232, v232
	v_exp_f32_e32 v233, v233
	s_mov_b32 s1, 0x800000
	s_add_i32 s73, s73, s40
	s_cmpk_lt_i32 s73, 0x200
	s_waitcnt vmcnt(4)
	v_lshlrev_b32_e32 v82, 16, v50
	s_waitcnt vmcnt(3)
	v_lshlrev_b32_e32 v84, 16, v54
	v_and_b32_e32 v85, 0xffff0000, v54
	v_and_b32_e32 v83, 0xffff0000, v50
	s_waitcnt vmcnt(0)
	v_cvt_f32_i32_e32 v49, v0
	v_mul_lo_u32 v0, v66, s9
	v_or_b32_e32 v0, v0, v2
	v_lshl_add_u32 v0, v0, 1, v229
	v_lshl_add_u64 v[66:67], v[66:67], 2, s[12:13]
	buffer_load_dwordx4 v[44:47], v0, s[88:91], 0 offen
	buffer_load_dwordx4 v[40:43], v0, s[88:91], 0 offen offset:128
	buffer_load_dwordx4 v[28:31], v0, s[88:91], 0 offen offset:1024
	s_nop 0
	buffer_load_dwordx4 v[0:3], v0, s[88:91], 0 offen offset:1152
	v_mul_f32_e32 v70, v109, v49
	global_load_dword v66, v[66:67], off
	v_mul_f32_e32 v71, 0.15915494, v70
	v_rndne_f32_e32 v71, v71
	v_fmac_f32_e32 v70, 0xc0c90000, v71
	v_fmac_f32_e32 v70, 0xbafdaa22, v71
	v_mul_f32_e32 v71, 0.15915494, v70
	v_sin_f32_e32 v70, v71
	v_cos_f32_e32 v72, v71
	v_mul_f32_e32 v71, v110, v49
	v_mul_f32_e32 v73, 0.15915494, v71
	v_mul_f32_e32 v74, v111, v49
	v_rndne_f32_e32 v73, v73
	v_mul_f32_e32 v75, 0.15915494, v74
	v_fmac_f32_e32 v71, 0xc0c90000, v73
	v_rndne_f32_e32 v75, v75
	v_fmac_f32_e32 v71, 0xbafdaa22, v73
	v_fmac_f32_e32 v74, 0xc0c90000, v75
	v_mul_f32_e32 v73, 0.15915494, v71
	v_fmac_f32_e32 v74, 0xbafdaa22, v75
	v_sin_f32_e32 v71, v73
	v_mul_f32_e32 v75, 0.15915494, v74
	v_cos_f32_e32 v73, v73
	v_sin_f32_e32 v74, v75
	v_cos_f32_e32 v76, v75
	v_mul_f32_e32 v75, v112, v49
	v_mul_f32_e32 v77, 0.15915494, v75
	v_rndne_f32_e32 v77, v77
	v_mul_f32_e32 v78, v113, v49
	v_fmac_f32_e32 v75, 0xc0c90000, v77
	v_mul_f32_e32 v79, 0.15915494, v78
	v_fmac_f32_e32 v75, 0xbafdaa22, v77
	v_rndne_f32_e32 v79, v79
	v_mul_f32_e32 v77, 0.15915494, v75
	v_fmac_f32_e32 v78, 0xc0c90000, v79
	v_sin_f32_e32 v75, v77
	v_fmac_f32_e32 v78, 0xbafdaa22, v79
	v_cos_f32_e32 v77, v77
	v_mul_f32_e32 v79, 0.15915494, v78
	v_sin_f32_e32 v78, v79
	v_cos_f32_e32 v80, v79
	s_waitcnt vmcnt(0)
; #define LAS __attribute__((address_space(3)))
; __device__ __forceinline__ unsigned pk2(float lo, float hi) { return pg8::cvt_pk_bf16(lo, hi); }
; __device__ __forceinline__ float bflo(unsigned w) { return __uint_as_float(w << 16); }
; __device__ __forceinline__ float bfhi(unsigned w) { return __uint_as_float(w & 0xffff0000u); }
; __device__ __forceinline__ float fexp2(float x) { return __builtin_amdgcn_exp2f(x); }
; __device__ __forceinline__ void ret_unit(LAS unsigned char* lds, int u, const bf16* PROJ, const int* pos, const float* dec_f, const float* dec_b, const bf16* ST,
;                                          const float* gn_w, const float* gn_b, bf16* MIX, int tid, const WsRef& wsr) {
;     ...
;         for (int e = 0; e < 8; ++e) { const int i = dc * 8 + e; const float inv = fexp2(-(float)i * 0.20762050593046015f); fast_sincos(p * inv, sn[e], cs[e]); }
;         u32x4 oq1, oq2, ok1, ok2;
; #pragma unroll
;         for (int e = 0; e < 4; ++e) { const int e0 = 2 * e, e1 = 2 * e + 1;
;             const float a0 = bflo(q1[e]), a1 = bfhi(q1[e]), b0 = bflo(q2[e]), b1 = bfhi(q2[e]);
;             oq1[e] = pk2(a0 * cs[e0] - b0 * sn[e0], a1 * cs[e1] - b1 * sn[e1]); oq2[e] = pk2(b0 * cs[e0] + a0 * sn[e0], b1 * cs[e1] + a1 * sn[e1]);
;             const float c0 = bflo(k1[e]) * 0.08838834764831845f, c1 = bfhi(k1[e]) * 0.08838834764831845f, d0 = bflo(k2[e]) * 0.08838834764831845f, d1 = bfhi(k2[e]) * 0.08838834764831845f;
;             ok1[e] = pk2(c0 * cs[e0] - d0 * sn[e0], c1 * cs[e1] - d1 * sn[e1]); ok2[e] = pk2(d0 * cs[e0] + c0 * sn[e0], d1 * cs[e1] + c1 * sn[e1]); }
;         *(LAS u32x4*)(Qs + j * LDT + dc * 8) = oq1; *(LAS u32x4*)(Qs + j * LDT + 64 + dc * 8) = oq2;
;         *(LAS u32x4*)(Ks + j * LDT + dc * 8) = ok1; *(LAS u32x4*)(Ks + j * LDT + 64 + dc * 8) = ok2; }
	v_cvt_f32_i32_e32 v88, v66
	v_mul_f32_e32 v66, v107, v49
	v_mul_f32_e32 v67, 0.15915494, v66
	v_rndne_f32_e32 v67, v67
	v_fmac_f32_e32 v66, 0xc0c90000, v67
	v_fmac_f32_e32 v66, 0xbafdaa22, v67
	v_mul_f32_e32 v67, 0.15915494, v66
	v_sin_f32_e32 v66, v67
	v_cos_f32_e32 v68, v67
	v_mul_f32_e32 v67, v108, v49
	v_mul_f32_e32 v69, 0.15915494, v67
	v_rndne_f32_e32 v69, v69
	v_fmac_f32_e32 v67, 0xc0c90000, v69
	v_fmac_f32_e32 v67, 0xbafdaa22, v69
	v_mul_f32_e32 v69, 0.15915494, v67
	v_sin_f32_e32 v67, v69
	v_cos_f32_e32 v69, v69
	v_mul_f32_e32 v49, v114, v49
	v_mul_f32_e32 v79, 0.15915494, v49
	v_pk_mul_f32 v[86:87], v[66:67], v[84:85]
	v_rndne_f32_e32 v79, v79
	v_pk_fma_f32 v[86:87], v[68:69], v[82:83], v[86:87] neg_lo:[0,0,1] neg_hi:[0,0,1]
	v_pk_mul_f32 v[82:83], v[66:67], v[82:83]
	v_cvt_pk_bf16_f32 v50, v86, v87
	v_pk_fma_f32 v[82:83], v[68:69], v[84:85], v[82:83]
	v_lshlrev_b32_e32 v84, 16, v62
	v_cvt_pk_bf16_f32 v54, v82, v83
	v_lshlrev_b32_e32 v82, 16, v58
	v_and_b32_e32 v83, 0xffff0000, v58
	v_and_b32_e32 v85, 0xffff0000, v62
	v_pk_mul_f32 v[82:83], v[82:83], s[10:11] op_sel_hi:[1,0]
	v_pk_mul_f32 v[84:85], v[84:85], s[10:11] op_sel_hi:[1,0]
	v_fmac_f32_e32 v49, 0xc0c90000, v79
	v_pk_mul_f32 v[86:87], v[84:85], v[66:67]
	v_pk_mul_f32 v[66:67], v[82:83], v[66:67]
	v_pk_fma_f32 v[86:87], v[82:83], v[68:69], v[86:87] neg_lo:[0,0,1] neg_hi:[0,0,1]
	v_pk_fma_f32 v[66:67], v[84:85], v[68:69], v[66:67]
	v_lshlrev_b32_e32 v68, 16, v55
	v_and_b32_e32 v69, 0xffff0000, v55
	v_cvt_pk_bf16_f32 v62, v66, v67
	v_lshlrev_b32_e32 v66, 16, v51
	v_and_b32_e32 v67, 0xffff0000, v51
	v_pk_mul_f32 v[82:83], v[70:71], v[68:69]
	v_fmac_f32_e32 v49, 0xbafdaa22, v79
	v_pk_fma_f32 v[82:83], v[72:73], v[66:67], v[82:83] neg_lo:[0,0,1] neg_hi:[0,0,1]
	v_pk_mul_f32 v[66:67], v[70:71], v[66:67]
	v_cvt_pk_bf16_f32 v51, v82, v83
	v_pk_fma_f32 v[66:67], v[72:73], v[68:69], v[66:67]
	v_lshlrev_b32_e32 v68, 16, v63
	v_and_b32_e32 v69, 0xffff0000, v63
	v_cvt_pk_bf16_f32 v55, v66, v67
	v_lshlrev_b32_e32 v66, 16, v59
	v_and_b32_e32 v67, 0xffff0000, v59
	v_pk_mul_f32 v[68:69], v[68:69], s[10:11] op_sel_hi:[1,0]
	v_pk_mul_f32 v[66:67], v[66:67], s[10:11] op_sel_hi:[1,0]
	v_pk_mul_f32 v[82:83], v[68:69], v[70:71]
	v_mul_f32_e32 v49, 0.15915494, v49
	v_pk_fma_f32 v[82:83], v[66:67], v[72:73], v[82:83] neg_lo:[0,0,1] neg_hi:[0,0,1]
	v_pk_mul_f32 v[66:67], v[66:67], v[70:71]
	v_sin_f32_e32 v79, v49
	v_pk_fma_f32 v[66:67], v[68:69], v[72:73], v[66:67]
	v_lshlrev_b32_e32 v68, 16, v56
	v_and_b32_e32 v69, 0xffff0000, v56
	v_cvt_pk_bf16_f32 v63, v66, v67
	v_lshlrev_b32_e32 v66, 16, v52
	v_and_b32_e32 v67, 0xffff0000, v52
	v_pk_mul_f32 v[70:71], v[74:75], v[68:69]
	v_cos_f32_e32 v81, v49
	v_pk_fma_f32 v[70:71], v[76:77], v[66:67], v[70:71] neg_lo:[0,0,1] neg_hi:[0,0,1]
	v_pk_mul_f32 v[66:67], v[74:75], v[66:67]
	v_cvt_pk_bf16_f32 v52, v70, v71
	v_pk_fma_f32 v[66:67], v[76:77], v[68:69], v[66:67]
	v_lshlrev_b32_e32 v68, 16, v64
	v_and_b32_e32 v69, 0xffff0000, v64
	v_cvt_pk_bf16_f32 v56, v66, v67
	v_lshlrev_b32_e32 v66, 16, v60
	v_and_b32_e32 v67, 0xffff0000, v60
	v_pk_mul_f32 v[68:69], v[68:69], s[10:11] op_sel_hi:[1,0]
	v_pk_mul_f32 v[66:67], v[66:67], s[10:11] op_sel_hi:[1,0]
	v_pk_mul_f32 v[70:71], v[68:69], v[74:75]
	v_mul_f32_e32 v49, v107, v88
	v_pk_fma_f32 v[70:71], v[66:67], v[76:77], v[70:71] neg_lo:[0,0,1] neg_hi:[0,0,1]
	v_pk_mul_f32 v[66:67], v[66:67], v[74:75]
	v_cvt_pk_bf16_f32 v60, v70, v71
	v_pk_fma_f32 v[66:67], v[68:69], v[76:77], v[66:67]
	v_lshlrev_b32_e32 v68, 16, v57
	v_and_b32_e32 v69, 0xffff0000, v57
	v_cvt_pk_bf16_f32 v64, v66, v67
	v_lshlrev_b32_e32 v66, 16, v53
	v_and_b32_e32 v67, 0xffff0000, v53
	v_pk_mul_f32 v[70:71], v[78:79], v[68:69]
	v_cvt_pk_bf16_f32 v58, v86, v87
	v_pk_fma_f32 v[70:71], v[80:81], v[66:67], v[70:71] neg_lo:[0,0,1] neg_hi:[0,0,1]
	v_pk_mul_f32 v[66:67], v[78:79], v[66:67]
	v_cvt_pk_bf16_f32 v53, v70, v71
	v_pk_fma_f32 v[66:67], v[80:81], v[68:69], v[66:67]
	v_lshlrev_b32_e32 v68, 16, v65
	v_and_b32_e32 v69, 0xffff0000, v65
	v_cvt_pk_bf16_f32 v57, v66, v67
	v_lshlrev_b32_e32 v66, 16, v61
	v_and_b32_e32 v67, 0xffff0000, v61
	v_pk_mul_f32 v[68:69], v[68:69], s[10:11] op_sel_hi:[1,0]
	v_pk_mul_f32 v[66:67], v[66:67], s[10:11] op_sel_hi:[1,0]
	v_pk_mul_f32 v[70:71], v[68:69], v[78:79]
	v_cvt_pk_bf16_f32 v59, v82, v83
	v_pk_fma_f32 v[70:71], v[66:67], v[80:81], v[70:71] neg_lo:[0,0,1] neg_hi:[0,0,1]
	v_pk_mul_f32 v[66:67], v[66:67], v[78:79]
	v_cvt_pk_bf16_f32 v61, v70, v71
	v_pk_fma_f32 v[66:67], v[68:69], v[80:81], v[66:67]
	v_lshlrev_b32_e32 v68, 16, v40
	v_cvt_pk_bf16_f32 v65, v66, v67
	ds_write_b128 v115, v[50:53]
	ds_write_b128 v115, v[54:57] offset:128
	ds_write_b128 v115, v[58:61] offset:34816
	ds_write_b128 v115, v[62:65] offset:34944
	v_mul_f32_e32 v50, 0.15915494, v49
	v_rndne_f32_e32 v50, v50
	v_fmac_f32_e32 v49, 0xc0c90000, v50
	v_fmac_f32_e32 v49, 0xbafdaa22, v50
	v_mul_f32_e32 v49, 0.15915494, v49
	v_sin_f32_e32 v50, v49
	v_cos_f32_e32 v52, v49
	v_mul_f32_e32 v49, v108, v88
	v_mul_f32_e32 v51, 0.15915494, v49
	v_rndne_f32_e32 v51, v51
	v_fmac_f32_e32 v49, 0xc0c90000, v51
	v_fmac_f32_e32 v49, 0xbafdaa22, v51
	v_mul_f32_e32 v49, 0.15915494, v49
	v_sin_f32_e32 v51, v49
	v_cos_f32_e32 v53, v49
	v_mul_f32_e32 v49, v109, v88
	v_mul_f32_e32 v54, 0.15915494, v49
	v_rndne_f32_e32 v54, v54
	v_fmac_f32_e32 v49, 0xc0c90000, v54
	v_fmac_f32_e32 v49, 0xbafdaa22, v54
	v_mul_f32_e32 v49, 0.15915494, v49
	v_sin_f32_e32 v54, v49
	v_cos_f32_e32 v56, v49
	v_mul_f32_e32 v49, v110, v88
	v_mul_f32_e32 v55, 0.15915494, v49
	v_rndne_f32_e32 v55, v55
	v_fmac_f32_e32 v49, 0xc0c90000, v55
	v_fmac_f32_e32 v49, 0xbafdaa22, v55
	v_mul_f32_e32 v49, 0.15915494, v49
; #define LAS __attribute__((address_space(3)))
; __device__ __forceinline__ unsigned pk2(float lo, float hi) { return pg8::cvt_pk_bf16(lo, hi); }
; __device__ __forceinline__ float bflo(unsigned w) { return __uint_as_float(w << 16); }
; __device__ __forceinline__ float bfhi(unsigned w) { return __uint_as_float(w & 0xffff0000u); }
; __device__ __forceinline__ u32x4 ws_load16(const WsRef& w, unsigned byte_off) { return __builtin_bit_cast(u32x4, __builtin_amdgcn_raw_buffer_load_b128(w.r, byte_off, 0, 0)); }
; __device__ __forceinline__ void ret_unit(LAS unsigned char* lds, int u, const bf16* PROJ, const int* pos, const float* dec_f, const float* dec_b, const bf16* ST,
;                                          const float* gn_w, const float* gn_b, bf16* MIX, int tid, const WsRef& wsr) {
;     ...
;     for (int ii = 0; ii < 2; ++ii) { const int it = tid + 512 * ii, dc = it & 7, j = it >> 3;
;         const u32x4 q1 = rq1[ii], q2 = rq2[ii], k1 = rk1[ii], k2 = rk2[ii];
;         const float p = rp[ii];
;         float sn[8], cs[8];
; #pragma unroll
;         for (int e = 0; e < 8; ++e) { const int i = dc * 8 + e; const float inv = fexp2(-(float)i * 0.20762050593046015f); fast_sincos(p * inv, sn[e], cs[e]); }
;         u32x4 oq1, oq2, ok1, ok2;
; #pragma unroll
;         for (int e = 0; e < 4; ++e) { const int e0 = 2 * e, e1 = 2 * e + 1;
;             const float a0 = bflo(q1[e]), a1 = bfhi(q1[e]), b0 = bflo(q2[e]), b1 = bfhi(q2[e]);
;             oq1[e] = pk2(a0 * cs[e0] - b0 * sn[e0], a1 * cs[e1] - b1 * sn[e1]); oq2[e] = pk2(b0 * cs[e0] + a0 * sn[e0], b1 * cs[e1] + a1 * sn[e1]);
;             const float c0 = bflo(k1[e]) * 0.08838834764831845f, c1 = bfhi(k1[e]) * 0.08838834764831845f, d0 = bflo(k2[e]) * 0.08838834764831845f, d1 = bfhi(k2[e]) * 0.08838834764831845f;
;             ok1[e] = pk2(c0 * cs[e0] - d0 * sn[e0], c1 * cs[e1] - d1 * sn[e1]); ok2[e] = pk2(d0 * cs[e0] + c0 * sn[e0], d1 * cs[e1] + c1 * sn[e1]); }
;         *(LAS u32x4*)(Qs + j * LDT + dc * 8) = oq1; *(LAS u32x4*)(Qs + j * LDT + 64 + dc * 8) = oq2;
;         *(LAS u32x4*)(Ks + j * LDT + dc * 8) = ok1; *(LAS u32x4*)(Ks + j * LDT + 64 + dc * 8) = ok2; }
; #pragma unroll
;     for (int ii = 0; ii < 4; ++ii) { const int it = tid + 512 * ii, ec = it & 15, j = it >> 4; rv[ii] = ws_load16(wsr, (unsigned)WS_PROJ + (unsigned)(((unsigned)(row0 + j) * INC + 1024 + h * 128 + ec * 8) * 2u)); }
	v_sin_f32_e32 v55, v49
	v_cos_f32_e32 v57, v49
	v_mul_f32_e32 v49, v111, v88
	v_mul_f32_e32 v58, 0.15915494, v49
	v_rndne_f32_e32 v58, v58
	v_fmac_f32_e32 v49, 0xc0c90000, v58
	v_fmac_f32_e32 v49, 0xbafdaa22, v58
	v_mul_f32_e32 v49, 0.15915494, v49
	v_sin_f32_e32 v58, v49
	v_cos_f32_e32 v60, v49
	v_mul_f32_e32 v49, v112, v88
	v_and_b32_e32 v69, 0xffff0000, v40
	v_mul_f32_e32 v59, 0.15915494, v49
	v_lshlrev_b32_e32 v66, 16, v44
	v_and_b32_e32 v67, 0xffff0000, v44
	v_pk_mul_f32 v[70:71], v[50:51], v[68:69]
	v_rndne_f32_e32 v59, v59
	v_pk_fma_f32 v[70:71], v[52:53], v[66:67], v[70:71] neg_lo:[0,0,1] neg_hi:[0,0,1]
	v_pk_mul_f32 v[66:67], v[50:51], v[66:67]
	v_fmac_f32_e32 v49, 0xc0c90000, v59
	v_pk_fma_f32 v[66:67], v[52:53], v[68:69], v[66:67]
	v_fmac_f32_e32 v49, 0xbafdaa22, v59
	v_cvt_pk_bf16_f32 v44, v66, v67
	v_lshlrev_b32_e32 v66, 16, v28
	v_and_b32_e32 v67, 0xffff0000, v28
	v_lshlrev_b32_e32 v68, 16, v0
	v_and_b32_e32 v69, 0xffff0000, v0
	v_mul_f32_e32 v49, 0.15915494, v49
	v_pk_mul_f32 v[66:67], v[66:67], s[10:11] op_sel_hi:[1,0]
	v_pk_mul_f32 v[68:69], v[68:69], s[10:11] op_sel_hi:[1,0]
	v_sin_f32_e32 v59, v49
	v_cos_f32_e32 v61, v49
	v_mul_f32_e32 v49, v113, v88
	v_cvt_pk_bf16_f32 v40, v70, v71
	v_pk_mul_f32 v[70:71], v[68:69], v[50:51]
	v_pk_mul_f32 v[50:51], v[66:67], v[50:51]
	v_mul_f32_e32 v62, 0.15915494, v49
	v_pk_fma_f32 v[70:71], v[66:67], v[52:53], v[70:71] neg_lo:[0,0,1] neg_hi:[0,0,1]
	v_pk_fma_f32 v[50:51], v[68:69], v[52:53], v[50:51]
	v_lshlrev_b32_e32 v52, 16, v41
	v_and_b32_e32 v53, 0xffff0000, v41
	v_rndne_f32_e32 v62, v62
	v_cvt_pk_bf16_f32 v28, v50, v51
	v_lshlrev_b32_e32 v50, 16, v45
	v_and_b32_e32 v51, 0xffff0000, v45
	v_pk_mul_f32 v[66:67], v[54:55], v[52:53]
	v_fmac_f32_e32 v49, 0xc0c90000, v62
	v_pk_fma_f32 v[66:67], v[56:57], v[50:51], v[66:67] neg_lo:[0,0,1] neg_hi:[0,0,1]
	v_pk_mul_f32 v[50:51], v[54:55], v[50:51]
	v_fmac_f32_e32 v49, 0xbafdaa22, v62
	v_pk_fma_f32 v[50:51], v[56:57], v[52:53], v[50:51]
	v_lshlrev_b32_e32 v52, 16, v1
	v_and_b32_e32 v53, 0xffff0000, v1
	v_mul_f32_e32 v49, 0.15915494, v49
	v_cvt_pk_bf16_f32 v45, v50, v51
	v_lshlrev_b32_e32 v50, 16, v29
	v_and_b32_e32 v51, 0xffff0000, v29
	v_pk_mul_f32 v[52:53], v[52:53], s[10:11] op_sel_hi:[1,0]
	v_sin_f32_e32 v62, v49
	v_cos_f32_e32 v64, v49
	v_mul_f32_e32 v49, v114, v88
	v_cvt_pk_bf16_f32 v41, v66, v67
	v_pk_mul_f32 v[50:51], v[50:51], s[10:11] op_sel_hi:[1,0]
	v_pk_mul_f32 v[66:67], v[52:53], v[54:55]
	v_mul_f32_e32 v63, 0.15915494, v49
	v_pk_fma_f32 v[66:67], v[50:51], v[56:57], v[66:67] neg_lo:[0,0,1] neg_hi:[0,0,1]
	v_pk_mul_f32 v[50:51], v[50:51], v[54:55]
	v_rndne_f32_e32 v63, v63
	v_pk_fma_f32 v[50:51], v[52:53], v[56:57], v[50:51]
	v_lshlrev_b32_e32 v52, 16, v42
	v_and_b32_e32 v53, 0xffff0000, v42
	v_fmac_f32_e32 v49, 0xc0c90000, v63
	v_cvt_pk_bf16_f32 v29, v50, v51
	v_lshlrev_b32_e32 v50, 16, v46
	v_and_b32_e32 v51, 0xffff0000, v46
	v_pk_mul_f32 v[54:55], v[58:59], v[52:53]
	v_fmac_f32_e32 v49, 0xbafdaa22, v63
	v_pk_fma_f32 v[54:55], v[60:61], v[50:51], v[54:55] neg_lo:[0,0,1] neg_hi:[0,0,1]
	v_pk_mul_f32 v[50:51], v[58:59], v[50:51]
	v_mul_f32_e32 v49, 0.15915494, v49
	v_pk_fma_f32 v[50:51], v[60:61], v[52:53], v[50:51]
	v_lshlrev_b32_e32 v52, 16, v2
	v_and_b32_e32 v53, 0xffff0000, v2
	v_sin_f32_e32 v63, v49
	v_cvt_pk_bf16_f32 v46, v50, v51
	v_lshlrev_b32_e32 v50, 16, v30
	v_and_b32_e32 v51, 0xffff0000, v30
	v_pk_mul_f32 v[52:53], v[52:53], s[10:11] op_sel_hi:[1,0]
	v_cos_f32_e32 v65, v49
	v_cvt_pk_bf16_f32 v42, v54, v55
	v_pk_mul_f32 v[50:51], v[50:51], s[10:11] op_sel_hi:[1,0]
	v_pk_mul_f32 v[54:55], v[52:53], v[58:59]
	v_cvt_pk_bf16_f32 v0, v70, v71
	v_pk_fma_f32 v[54:55], v[50:51], v[60:61], v[54:55] neg_lo:[0,0,1] neg_hi:[0,0,1]
	v_pk_mul_f32 v[50:51], v[50:51], v[58:59]
	v_cvt_pk_bf16_f32 v2, v54, v55
	v_pk_fma_f32 v[50:51], v[52:53], v[60:61], v[50:51]
	v_lshlrev_b32_e32 v52, 16, v43
	v_and_b32_e32 v53, 0xffff0000, v43
	v_cvt_pk_bf16_f32 v30, v50, v51
	v_lshlrev_b32_e32 v50, 16, v47
	v_and_b32_e32 v51, 0xffff0000, v47
	v_pk_mul_f32 v[54:55], v[62:63], v[52:53]
	v_cvt_pk_bf16_f32 v1, v66, v67
	v_pk_fma_f32 v[54:55], v[64:65], v[50:51], v[54:55] neg_lo:[0,0,1] neg_hi:[0,0,1]
	v_pk_mul_f32 v[50:51], v[62:63], v[50:51]
	v_cvt_pk_bf16_f32 v43, v54, v55
	v_pk_fma_f32 v[50:51], v[64:65], v[52:53], v[50:51]
	v_lshlrev_b32_e32 v52, 16, v3
	v_and_b32_e32 v53, 0xffff0000, v3
	v_cvt_pk_bf16_f32 v47, v50, v51
	v_lshlrev_b32_e32 v50, 16, v31
	v_and_b32_e32 v51, 0xffff0000, v31
	v_pk_mul_f32 v[52:53], v[52:53], s[10:11] op_sel_hi:[1,0]
	v_pk_mul_f32 v[50:51], v[50:51], s[10:11] op_sel_hi:[1,0]
	v_pk_mul_f32 v[54:55], v[52:53], v[62:63]
	v_add_u32_e32 v49, v124, v125
	v_pk_fma_f32 v[54:55], v[50:51], v[64:65], v[54:55] neg_lo:[0,0,1] neg_hi:[0,0,1]
	v_pk_mul_f32 v[50:51], v[50:51], v[62:63]
	v_cvt_pk_bf16_f32 v3, v54, v55
	v_pk_fma_f32 v[50:51], v[52:53], v[64:65], v[50:51]
	v_cndmask_b32_e64 v86, v105, v230, s[66:67]
	v_cvt_pk_bf16_f32 v31, v50, v51
	ds_write_b128 v116, v[40:43]
	ds_write_b128 v116, v[44:47] offset:128
	ds_write_b128 v116, v[0:3] offset:34816
	ds_write_b128 v116, v[28:31] offset:34944
	v_or_b32_e32 v44, s0, v222
	v_or_b32_e32 v0, s4, v99
	v_mad_u64_u32 v[0:1], s[68:69], v0, s9, v[44:45]
	v_lshl_add_u32 v0, v0, 1, v229
	buffer_load_dwordx4 v[0:3], v0, s[88:91], 0 offen
	v_or_b32_e32 v28, s4, v117
	v_mad_u64_u32 v[28:29], s[68:69], v28, s9, v[44:45]
	v_lshl_add_u32 v28, v28, 1, v229
	buffer_load_dwordx4 v[28:31], v28, s[88:91], 0 offen
	v_or_b32_e32 v40, s4, v118
	v_mad_u64_u32 v[40:41], s[68:69], v40, s9, v[44:45]
	v_lshl_add_u32 v40, v40, 1, v229
	buffer_load_dwordx4 v[40:43], v40, s[88:91], 0 offen
	v_add_u32_e32 v45, s4, v119
	v_mad_u64_u32 v[44:45], s[68:69], v45, s9, v[44:45]
	v_lshl_add_u32 v44, v44, 1, v229
	buffer_load_dwordx4 v[44:47], v44, s[88:91], 0 offen
	s_waitcnt vmcnt(3)
; #define LAS __attribute__((address_space(3)))
; __device__ __forceinline__ float fexp2(float x) { return __builtin_amdgcn_exp2f(x); }
; #define MFMA16(a, b, c) __builtin_amdgcn_mfma_f32_16x16x32_bf16((a), (b), (c), 0, 0, 0)
; __device__ __forceinline__ void ret_unit(LAS unsigned char* lds, int u, const bf16* PROJ, const int* pos, const float* dec_f, const float* dec_b, const bf16* ST,
;                                          const float* gn_w, const float* gn_b, bf16* MIX, int tid, const WsRef& wsr) {
;     ...
;     for (int ii = 0; ii < 4; ++ii) { const int it = tid + 512 * ii, ec = it & 15, j = it >> 4; const u32x4 w = rv[ii];
;         const int jsw = (((j >> 3) ^ (ec & 7)) << 3) | (j & 7);
; #pragma unroll
;         for (int e = 0; e < 4; ++e) { VT[(ec * 8 + 2 * e) * LDT + jsw] = (bf16)(w[e] & 0xffffu); VT[(ec * 8 + 2 * e + 1) * LDT + jsw] = (bf16)(w[e] >> 16); } }
;     __syncthreads();
;     const int q = wave * 16 + fr;
;     bf16x8 qf[4];
; #pragma unroll
;     for (int kk = 0; kk < 4; ++kk) qf[kk] = *(const LAS bf16x8*)(Qs + q * LDT + kk * 32 + fq * 8);
;     f32x4 s[8];
; #pragma unroll
;     for (int n = 0; n < 8; ++n) s[n] = (f32x4){0.f, 0.f, 0.f, 0.f};
; #pragma unroll
;     for (int kk = 0; kk < 4; ++kk)
; #pragma unroll
;         for (int n = 0; n < 8; ++n) { const bf16x8 kf = *(const LAS bf16x8*)(Ks + (n * 16 + fr) * LDT + kk * 32 + fq * 8); s[n] = MFMA16(kf, qf[kk], s[n]); }
;     bf16x8 pf[4];
; #pragma unroll
;     for (int n = 0; n < 8; ++n) {
; #pragma unroll
;         for (int r = 0; r < 4; ++r) { const int key = n * 16 + 4 * fq + r; const int df = q - key; const float f = df >= 0 ? fexp2(lgf2 * (float)df) : fexp2(lgb2 * (float)(-df)); s[n][r] *= f; } }
	ds_write_b16 v120, v0
	ds_write_b16_d16_hi v120, v0 offset:272
	ds_write_b16 v120, v1 offset:544
	ds_write_b16_d16_hi v120, v1 offset:816
	ds_write_b16 v120, v2 offset:1088
	ds_write_b16_d16_hi v120, v2 offset:1360
	ds_write_b16 v120, v3 offset:1632
	ds_write_b16_d16_hi v120, v3 offset:1904
	s_waitcnt vmcnt(2)
	ds_write_b16 v121, v28
	ds_write_b16_d16_hi v121, v28 offset:272
	ds_write_b16 v121, v29 offset:544
	ds_write_b16_d16_hi v121, v29 offset:816
	ds_write_b16 v121, v30 offset:1088
	ds_write_b16_d16_hi v121, v30 offset:1360
	ds_write_b16 v121, v31 offset:1632
	ds_write_b16_d16_hi v121, v31 offset:1904
	s_waitcnt vmcnt(1)
	ds_write_b16 v122, v40
	ds_write_b16_d16_hi v122, v40 offset:272
	ds_write_b16 v122, v41 offset:544
	ds_write_b16_d16_hi v122, v41 offset:816
	ds_write_b16 v122, v42 offset:1088
	ds_write_b16_d16_hi v122, v42 offset:1360
	ds_write_b16 v122, v43 offset:1632
	ds_write_b16_d16_hi v122, v43 offset:1904
	s_waitcnt vmcnt(0)
	ds_write_b16 v123, v44
	ds_write_b16_d16_hi v123, v44 offset:272
	ds_write_b16 v123, v45 offset:544
	ds_write_b16_d16_hi v123, v45 offset:816
	ds_write_b16 v123, v46 offset:1088
	ds_write_b16_d16_hi v123, v46 offset:1360
	ds_write_b16 v123, v47 offset:1632
	ds_write_b16_d16_hi v123, v47 offset:1904
	s_waitcnt lgkmcnt(0)
	s_barrier
	ds_read_b128 v[44:47], v225
	ds_read_b128 v[40:43], v225 offset:64
	ds_read_b128 v[28:31], v225 offset:128
	ds_read_b128 v[0:3], v225 offset:192
	ds_read_b128 v[50:53], v226 offset:34816
	ds_read_b128 v[54:57], v226 offset:39168
	ds_read_b128 v[82:85], v226 offset:34880
	s_waitcnt lgkmcnt(2)
	v_mfma_f32_16x16x32_bf16 v[50:53], v[50:53], v[44:47], 0
	ds_read_b128 v[58:61], v226 offset:43520
	ds_read_b128 v[62:65], v226 offset:47872
	ds_read_b128 v[66:69], v226 offset:52224
	s_waitcnt lgkmcnt(3)
	v_mfma_f32_16x16x32_bf16 v[50:53], v[82:85], v[40:43], v[50:53]
	ds_read_b128 v[82:85], v226 offset:39232
	ds_read_b128 v[70:73], v49 offset:34816
	ds_read_b128 v[74:77], v49 offset:39168
	v_mfma_f32_16x16x32_bf16 v[54:57], v[54:57], v[44:47], 0
	ds_read_b128 v[78:81], v49 offset:43520
	v_cndmask_b32_e64 v87, v105, v230, s[26:27]
	v_cndmask_b32_e64 v88, v105, v230, s[28:29]
	s_waitcnt lgkmcnt(3)
	v_mfma_f32_16x16x32_bf16 v[54:57], v[82:85], v[40:43], v[54:57]
	ds_read_b128 v[82:85], v226 offset:43584
	v_mul_f32_e32 v86, v86, v134
	v_mul_f32_e32 v87, v87, v135
	v_mfma_f32_16x16x32_bf16 v[58:61], v[58:61], v[44:47], 0
	v_mul_f32_e32 v88, v88, v136
	v_exp_f32_e32 v86, v86
	v_exp_f32_e32 v87, v87
	s_waitcnt lgkmcnt(0)
	v_mfma_f32_16x16x32_bf16 v[58:61], v[82:85], v[40:43], v[58:61]
	ds_read_b128 v[82:85], v226 offset:47936
	v_exp_f32_e32 v88, v88
	v_readlane_b32 s68, v255, 4
	v_mfma_f32_16x16x32_bf16 v[62:65], v[62:65], v[44:47], 0
	v_readlane_b32 s69, v255, 5
	s_waitcnt lgkmcnt(0)
	v_mfma_f32_16x16x32_bf16 v[62:65], v[82:85], v[40:43], v[62:65]
	ds_read_b128 v[82:85], v226 offset:52288
	v_cndmask_b32_e64 v239, v105, v230, s[68:69]
	v_readlane_b32 s68, v255, 50
	v_mfma_f32_16x16x32_bf16 v[66:69], v[66:69], v[44:47], 0
	v_readlane_b32 s69, v255, 51
	v_mul_f32_e32 v239, v239, v155
	v_exp_f32_e32 v239, v239
	s_waitcnt lgkmcnt(0)
	v_mfma_f32_16x16x32_bf16 v[66:69], v[82:85], v[40:43], v[66:69]
	ds_read_b128 v[82:85], v49 offset:34880
	v_cndmask_b32_e64 v240, v105, v230, s[68:69]
	v_readlane_b32 s68, v255, 52
	v_mfma_f32_16x16x32_bf16 v[70:73], v[70:73], v[44:47], 0
	v_readlane_b32 s69, v255, 53
	v_mul_f32_e32 v240, v240, v156
	v_exp_f32_e32 v240, v240
	s_waitcnt lgkmcnt(0)
	v_mfma_f32_16x16x32_bf16 v[70:73], v[82:85], v[40:43], v[70:73]
	ds_read_b128 v[82:85], v49 offset:39232
	v_cndmask_b32_e64 v241, v105, v230, s[68:69]
	v_readlane_b32 s68, v255, 54
	v_mfma_f32_16x16x32_bf16 v[74:77], v[74:77], v[44:47], 0
	v_readlane_b32 s69, v255, 55
	v_mul_f32_e32 v241, v241, v157
	v_exp_f32_e32 v241, v241
	s_waitcnt lgkmcnt(0)
	v_mfma_f32_16x16x32_bf16 v[74:77], v[82:85], v[40:43], v[74:77]
	ds_read_b128 v[82:85], v49 offset:43584
	v_cndmask_b32_e64 v242, v105, v230, s[68:69]
	v_readlane_b32 s68, v255, 56
	v_mfma_f32_16x16x32_bf16 v[78:81], v[78:81], v[44:47], 0
	v_readlane_b32 s69, v255, 57
	v_mul_f32_e32 v242, v242, v158
	v_exp_f32_e32 v242, v242
	s_waitcnt lgkmcnt(0)
	v_mfma_f32_16x16x32_bf16 v[78:81], v[82:85], v[40:43], v[78:81]
	ds_read_b128 v[82:85], v226 offset:34944
	v_cndmask_b32_e64 v243, v105, v230, s[68:69]
	v_mul_f32_e32 v243, v243, v159
	s_waitcnt lgkmcnt(0)
	v_mfma_f32_16x16x32_bf16 v[50:53], v[82:85], v[28:31], v[50:53]
	ds_read_b128 v[82:85], v226 offset:39296
	v_exp_f32_e32 v243, v243
	s_waitcnt lgkmcnt(0)
	v_mfma_f32_16x16x32_bf16 v[54:57], v[82:85], v[28:31], v[54:57]
	ds_read_b128 v[82:85], v226 offset:43648
	s_waitcnt lgkmcnt(0)
	v_mfma_f32_16x16x32_bf16 v[58:61], v[82:85], v[28:31], v[58:61]
	ds_read_b128 v[82:85], v226 offset:48000
	s_waitcnt lgkmcnt(0)
	v_mfma_f32_16x16x32_bf16 v[62:65], v[82:85], v[28:31], v[62:65]
	ds_read_b128 v[82:85], v226 offset:52352
	s_waitcnt lgkmcnt(0)
	v_mfma_f32_16x16x32_bf16 v[66:69], v[82:85], v[28:31], v[66:69]
	ds_read_b128 v[82:85], v49 offset:34944
	s_waitcnt lgkmcnt(0)
	v_mfma_f32_16x16x32_bf16 v[70:73], v[82:85], v[28:31], v[70:73]
	ds_read_b128 v[82:85], v49 offset:39296
	s_waitcnt lgkmcnt(0)
	v_mfma_f32_16x16x32_bf16 v[74:77], v[82:85], v[28:31], v[74:77]
	ds_read_b128 v[82:85], v49 offset:43648
	s_waitcnt lgkmcnt(0)
	v_mfma_f32_16x16x32_bf16 v[78:81], v[82:85], v[28:31], v[78:81]
	ds_read_b128 v[82:85], v226 offset:35008
	s_waitcnt lgkmcnt(0)
	v_mfma_f32_16x16x32_bf16 v[50:53], v[82:85], v[0:3], v[50:53]
	ds_read_b128 v[82:85], v226 offset:39360
	s_waitcnt lgkmcnt(0)
; #define LAS __attribute__((address_space(3)))
; __device__ __forceinline__ unsigned pk2(float lo, float hi) { return pg8::cvt_pk_bf16(lo, hi); }
; __device__ __forceinline__ float fexp2(float x) { return __builtin_amdgcn_exp2f(x); }
; #define MFMA16(a, b, c) __builtin_amdgcn_mfma_f32_16x16x32_bf16((a), (b), (c), 0, 0, 0)
; __device__ __forceinline__ void ret_unit(LAS unsigned char* lds, int u, const bf16* PROJ, const int* pos, const float* dec_f, const float* dec_b, const bf16* ST,
;                                          const float* gn_w, const float* gn_b, bf16* MIX, int tid, const WsRef& wsr) {
;     ...
;         for (int r = 0; r < 4; ++r) { const int key = n * 16 + 4 * fq + r; const int df = q - key; const float f = df >= 0 ? fexp2(lgf2 * (float)df) : fexp2(lgb2 * (float)(-df)); s[n][r] *= f; } }
; #pragma unroll
;     for (int kk = 0; kk < 4; ++kk) { u32x4 w; w.x = pk2(s[2 * kk][0], s[2 * kk][1]); w.y = pk2(s[2 * kk][2], s[2 * kk][3]); w.z = pk2(s[2 * kk + 1][0], s[2 * kk + 1][1]); w.w = pk2(s[2 * kk + 1][2], s[2 * kk + 1][3]);
;         pf[kk] = __builtin_bit_cast(bf16x8, w); }
;     f32x4 o[8];
; #pragma unroll
;     for (int n = 0; n < 8; ++n) o[n] = (f32x4){0.f, 0.f, 0.f, 0.f};
; #pragma unroll
;     for (int kk = 0; kk < 4; ++kk)
; #pragma unroll
;         for (int n = 0; n < 8; ++n) { const int sw = (2 * n + (fr >> 3)) & 7, jc = kk * 4 + (fq >> 1); const LAS bf16* vr = VT + (n * 16 + fr) * LDT + 4 * (fq & 1);
;             const u32x2 lo = *(const LAS u32x2*)(vr + ((jc ^ sw) << 3)), hi = *(const LAS u32x2*)(vr + (((jc + 2) ^ sw) << 3)); u32x4 w; w.x = lo.x; w.y = lo.y; w.z = hi.x; w.w = hi.y;
;             o[n] = MFMA16(__builtin_bit_cast(bf16x8, w), pf[kk], o[n]); }
	v_mfma_f32_16x16x32_bf16 v[54:57], v[82:85], v[0:3], v[54:57]
	ds_read_b128 v[82:85], v226 offset:43712
	s_nop 6
	v_pk_mul_f32 v[56:57], v[86:87], v[56:57]
	s_waitcnt lgkmcnt(0)
	v_mfma_f32_16x16x32_bf16 v[58:61], v[82:85], v[0:3], v[58:61]
	ds_read_b128 v[82:85], v226 offset:48064
	s_nop 6
	v_pk_mul_f32 v[58:59], v[88:89], v[58:59]
	s_waitcnt lgkmcnt(0)
	v_mfma_f32_16x16x32_bf16 v[62:65], v[82:85], v[0:3], v[62:65]
	ds_read_b128 v[82:85], v226 offset:52416
	v_pk_mul_f32 v[88:89], v[90:91], v[60:61]
	s_nop 5
	v_pk_mul_f32 v[64:65], v[94:95], v[64:65]
	s_waitcnt lgkmcnt(0)
	v_mfma_f32_16x16x32_bf16 v[66:69], v[82:85], v[0:3], v[66:69]
	ds_read_b128 v[82:85], v49 offset:35008
	v_pk_mul_f32 v[92:93], v[92:93], v[62:63]
	v_cvt_pk_bf16_f32 v63, v56, v57
	v_cvt_pk_bf16_f32 v56, v58, v59
	v_cvt_pk_bf16_f32 v59, v64, v65
	v_add_u32_e32 v64, v160, v161
	ds_read_b64 v[64:65], v64
	s_waitcnt lgkmcnt(1)
	v_mfma_f32_16x16x32_bf16 v[70:73], v[82:85], v[0:3], v[70:73]
	ds_read_b128 v[82:85], v49 offset:39360
	v_cvt_pk_bf16_f32 v58, v92, v93
	v_add_u32_e32 v92, v175, v170
	ds_read_b64 v[92:93], v92
	s_waitcnt lgkmcnt(1)
	v_mfma_f32_16x16x32_bf16 v[74:77], v[82:85], v[0:3], v[74:77]
	ds_read_b128 v[82:85], v49 offset:43712
	v_add_u32_e32 v94, v175, v171
	ds_read_b64 v[94:95], v94
	s_waitcnt lgkmcnt(1)
	v_mfma_f32_16x16x32_bf16 v[78:81], v[82:85], v[0:3], v[78:81]
	v_cndmask_b32_e64 v49, v105, v230, s[44:45]
	v_cndmask_b32_e64 v82, v105, v230, s[46:47]
	v_cndmask_b32_e64 v83, v105, v230, s[48:49]
	v_mul_f32_e32 v49, v49, v129
	v_mul_f32_e32 v82, v82, v231
	v_mul_f32_e32 v83, v83, v252
	v_exp_f32_e32 v49, v49
	v_exp_f32_e32 v82, v82
	v_exp_f32_e32 v83, v83
	v_pk_mul_f32 v[66:67], v[130:131], v[66:67]
	v_pk_mul_f32 v[48:49], v[48:49], v[50:51]
	v_cndmask_b32_e64 v84, v105, v230, s[50:51]
	v_pk_mul_f32 v[50:51], v[82:83], v[52:53]
	v_cvt_pk_bf16_f32 v52, v66, v67
	v_add_u32_e32 v66, v160, v162
	ds_read_b64 v[66:67], v66
	v_cndmask_b32_e64 v85, v105, v230, s[52:53]
	v_mul_f32_e32 v84, v84, v253
	v_mul_f32_e32 v85, v85, v254
	v_exp_f32_e32 v84, v84
	v_exp_f32_e32 v85, v85
	v_cvt_pk_bf16_f32 v60, v48, v49
	v_cvt_pk_bf16_f32 v61, v50, v51
	v_pk_mul_f32 v[80:81], v[242:243], v[80:81]
	v_pk_mul_f32 v[54:55], v[84:85], v[54:55]
	v_cvt_pk_bf16_f32 v51, v80, v81
	v_cvt_pk_bf16_f32 v62, v54, v55
	v_cvt_pk_bf16_f32 v57, v88, v89
	v_pk_mul_f32 v[78:79], v[240:241], v[78:79]
	s_waitcnt lgkmcnt(0)
	v_mfma_f32_16x16x32_bf16 v[84:87], v[64:67], v[60:63], 0
	v_add_u32_e32 v64, v163, v164
	v_add_u32_e32 v66, v163, v165
	ds_read_b64 v[64:65], v64
	ds_read_b64 v[66:67], v66
	s_waitcnt lgkmcnt(0)
	v_mfma_f32_16x16x32_bf16 v[80:83], v[64:67], v[60:63], 0
	v_add_u32_e32 v64, v166, v167
	v_add_u32_e32 v66, v166, v168
	ds_read_b64 v[64:65], v64
	ds_read_b64 v[66:67], v66
	s_waitcnt lgkmcnt(0)
	v_mfma_f32_16x16x32_bf16 v[88:91], v[64:67], v[60:63], 0
	v_add_u32_e32 v64, v169, v170
	v_add_u32_e32 v66, v169, v171
	ds_read_b64 v[64:65], v64
	ds_read_b64 v[66:67], v66
	v_pk_mul_f32 v[76:77], v[238:239], v[76:77]
	v_cvt_pk_bf16_f32 v50, v78, v79
	v_cvt_pk_bf16_f32 v49, v76, v77
	s_waitcnt lgkmcnt(0)
	v_mfma_f32_16x16x32_bf16 v[76:79], v[64:67], v[60:63], 0
	v_add_u32_e32 v64, v172, v161
	v_add_u32_e32 v66, v172, v162
	ds_read_b64 v[64:65], v64
	ds_read_b64 v[66:67], v66
	v_pk_mul_f32 v[74:75], v[236:237], v[74:75]
	v_pk_mul_f32 v[72:73], v[234:235], v[72:73]
	v_cvt_pk_bf16_f32 v48, v74, v75
	v_cvt_pk_bf16_f32 v55, v72, v73
	s_waitcnt lgkmcnt(0)
	v_mfma_f32_16x16x32_bf16 v[72:75], v[64:67], v[60:63], 0
	v_add_u32_e32 v64, v173, v164
	v_add_u32_e32 v66, v173, v165
	ds_read_b64 v[64:65], v64
	ds_read_b64 v[66:67], v66
	v_pk_mul_f32 v[70:71], v[232:233], v[70:71]
	v_pk_mul_f32 v[68:69], v[132:133], v[68:69]
	v_cvt_pk_bf16_f32 v54, v70, v71
	v_cvt_pk_bf16_f32 v53, v68, v69
	s_waitcnt lgkmcnt(0)
	v_mfma_f32_16x16x32_bf16 v[68:71], v[64:67], v[60:63], 0
	v_add_u32_e32 v64, v174, v167
	v_add_u32_e32 v66, v174, v168
	ds_read_b64 v[64:65], v64
	ds_read_b64 v[66:67], v66
	s_waitcnt lgkmcnt(0)
	v_mfma_f32_16x16x32_bf16 v[64:67], v[64:67], v[60:63], 0
	v_mfma_f32_16x16x32_bf16 v[60:63], v[92:95], v[60:63], 0
	v_add_u32_e32 v92, v160, v176
	v_add_u32_e32 v94, v160, v177
	ds_read_b64 v[92:93], v92
	ds_read_b64 v[94:95], v94
	s_waitcnt lgkmcnt(0)
	v_mfma_f32_16x16x32_bf16 v[84:87], v[92:95], v[56:59], v[84:87]
	v_add_u32_e32 v92, v163, v178
	v_add_u32_e32 v94, v163, v179
	ds_read_b64 v[92:93], v92
	ds_read_b64 v[94:95], v94
	s_waitcnt lgkmcnt(0)
	v_mfma_f32_16x16x32_bf16 v[80:83], v[92:95], v[56:59], v[80:83]
	v_add_u32_e32 v92, v166, v180
	v_add_u32_e32 v94, v166, v181
	ds_read_b64 v[92:93], v92
	ds_read_b64 v[94:95], v94
	s_waitcnt lgkmcnt(0)
	v_mfma_f32_16x16x32_bf16 v[88:91], v[92:95], v[56:59], v[88:91]
	v_add_u32_e32 v92, v169, v182
	v_add_u32_e32 v94, v169, v183
	ds_read_b64 v[92:93], v92
	ds_read_b64 v[94:95], v94
	s_waitcnt lgkmcnt(0)
	v_mfma_f32_16x16x32_bf16 v[92:95], v[92:95], v[56:59], v[76:79]
	s_nop 2
	v_add_u32_e32 v76, v172, v176
	v_add_u32_e32 v78, v172, v177
	ds_read_b64 v[76:77], v76
	ds_read_b64 v[78:79], v78
	s_waitcnt lgkmcnt(0)
	v_mfma_f32_16x16x32_bf16 v[72:75], v[76:79], v[56:59], v[72:75]
	v_add_u32_e32 v76, v173, v178
	v_add_u32_e32 v78, v173, v179
	ds_read_b64 v[76:77], v76
	ds_read_b64 v[78:79], v78
	s_waitcnt lgkmcnt(0)
	v_mfma_f32_16x16x32_bf16 v[68:71], v[76:79], v[56:59], v[68:71]
	v_add_u32_e32 v76, v174, v180
	v_add_u32_e32 v78, v174, v181
	ds_read_b64 v[76:77], v76
	ds_read_b64 v[78:79], v78
	s_waitcnt lgkmcnt(0)
	v_mfma_f32_16x16x32_bf16 v[64:67], v[76:79], v[56:59], v[64:67]
	v_add_u32_e32 v76, v175, v182
	v_add_u32_e32 v78, v175, v183
	ds_read_b64 v[76:77], v76
	ds_read_b64 v[78:79], v78
	s_waitcnt lgkmcnt(0)
; #define LAS __attribute__((address_space(3)))
; #define MFMA16(a, b, c) __builtin_amdgcn_mfma_f32_16x16x32_bf16((a), (b), (c), 0, 0, 0)
; __device__ __forceinline__ void ret_unit(LAS unsigned char* lds, int u, const bf16* PROJ, const int* pos, const float* dec_f, const float* dec_b, const bf16* ST,
;                                          const float* gn_w, const float* gn_b, bf16* MIX, int tid, const WsRef& wsr) {
;     ...
; #pragma unroll
;     for (int kk = 0; kk < 4; ++kk)
; #pragma unroll
;         for (int n = 0; n < 8; ++n) { const int sw = (2 * n + (fr >> 3)) & 7, jc = kk * 4 + (fq >> 1); const LAS bf16* vr = VT + (n * 16 + fr) * LDT + 4 * (fq & 1);
;             const u32x2 lo = *(const LAS u32x2*)(vr + ((jc ^ sw) << 3)), hi = *(const LAS u32x2*)(vr + (((jc + 2) ^ sw) << 3)); u32x4 w; w.x = lo.x; w.y = lo.y; w.z = hi.x; w.w = hi.y;
;             o[n] = MFMA16(__builtin_bit_cast(bf16x8, w), pf[kk], o[n]); }
;     __syncthreads();
; #pragma unroll
;     for (int i = 0; i < 4; ++i) { const int id = tid + 512 * i, e = id >> 4, dch = id & 15;
;         *(LAS u32x4*)(Ks + e * LDT + dch * 8) = sf[i]; *(LAS u32x4*)(VT + e * LDT + dch * 8) = sb[i]; }
;     __syncthreads();
;     {
;         f32x4 tf[8], tb[8];
; #pragma unroll
;         for (int n = 0; n < 8; ++n) { tf[n] = (f32x4){0.f, 0.f, 0.f, 0.f}; tb[n] = (f32x4){0.f, 0.f, 0.f, 0.f}; }
; #pragma unroll
;         for (int kk = 0; kk < 4; ++kk)
; #pragma unroll
;             for (int n = 0; n < 8; ++n) { const bf16x8 yf = *(const LAS bf16x8*)(Ks + (n * 16 + fr) * LDT + kk * 32 + fq * 8); const bf16x8 yb = *(const LAS bf16x8*)(VT + (n * 16 + fr) * LDT + kk * 32 + fq * 8);
;                 tf[n] = MFMA16(yf, qf[kk], tf[n]); tb[n] = MFMA16(yb, qf[kk], tb[n]); }
	v_mfma_f32_16x16x32_bf16 v[56:59], v[76:79], v[56:59], v[60:63]
	v_add_u32_e32 v76, v163, v186
	v_add_u32_e32 v78, v163, v187
	ds_read_b64 v[76:77], v76
	ds_read_b64 v[78:79], v78
	s_waitcnt lgkmcnt(0)
	v_mfma_f32_16x16x32_bf16 v[76:79], v[76:79], v[52:55], v[80:83]
	s_nop 2
	v_add_u32_e32 v80, v166, v188
	v_add_u32_e32 v82, v166, v189
	ds_read_b64 v[80:81], v80
	ds_read_b64 v[82:83], v82
	s_waitcnt lgkmcnt(0)
	v_mfma_f32_16x16x32_bf16 v[80:83], v[80:83], v[52:55], v[88:91]
	s_nop 2
	v_add_u32_e32 v88, v172, v184
	v_add_u32_e32 v90, v172, v185
	ds_read_b64 v[88:89], v88
	ds_read_b64 v[90:91], v90
	s_waitcnt lgkmcnt(0)
	v_mfma_f32_16x16x32_bf16 v[72:75], v[88:91], v[52:55], v[72:75]
	v_add_u32_e32 v88, v173, v186
	v_add_u32_e32 v90, v173, v187
	v_add_u32_e32 v60, v160, v184
	v_add_u32_e32 v62, v160, v185
	ds_read_b64 v[88:89], v88
	ds_read_b64 v[90:91], v90
	ds_read_b64 v[60:61], v60
	ds_read_b64 v[62:63], v62
	s_waitcnt lgkmcnt(2)
	v_mfma_f32_16x16x32_bf16 v[88:91], v[88:91], v[52:55], v[68:71]
	s_nop 2
	v_add_u32_e32 v68, v174, v188
	v_add_u32_e32 v70, v174, v189
	ds_read_b64 v[68:69], v68
	ds_read_b64 v[70:71], v70
	s_waitcnt lgkmcnt(2)
	v_mfma_f32_16x16x32_bf16 v[60:63], v[60:63], v[52:55], v[84:87]
	s_nop 2
	v_add_u32_e32 v84, v169, v190
	v_add_u32_e32 v86, v169, v191
	ds_read_b64 v[84:85], v84
	ds_read_b64 v[86:87], v86
	s_waitcnt lgkmcnt(0)
	v_mfma_f32_16x16x32_bf16 v[84:87], v[84:87], v[52:55], v[92:95]
	v_mfma_f32_16x16x32_bf16 v[92:95], v[68:71], v[52:55], v[64:67]
	v_add_u32_e32 v68, v172, v192
	v_add_u32_e32 v70, v172, v193
	ds_read_b64 v[68:69], v68
	ds_read_b64 v[70:71], v70
	v_add_u32_e32 v64, v175, v190
	v_add_u32_e32 v66, v175, v191
	ds_read_b64 v[64:65], v64
	ds_read_b64 v[66:67], v66
	s_waitcnt lgkmcnt(0)
	v_mfma_f32_16x16x32_bf16 v[232:235], v[64:67], v[52:55], v[56:59]
	v_add_u32_e32 v52, v160, v192
	v_add_u32_e32 v54, v160, v193
	ds_read_b64 v[52:53], v52
	ds_read_b64 v[54:55], v54
	v_add_u32_e32 v56, v163, v194
	v_add_u32_e32 v58, v163, v195
	ds_read_b64 v[56:57], v56
	ds_read_b64 v[58:59], v58
	s_waitcnt lgkmcnt(2)
	v_mfma_f32_16x16x32_bf16 v[52:55], v[52:55], v[48:51], v[60:63]
	s_nop 2
	v_add_u32_e32 v60, v166, v196
	v_add_u32_e32 v62, v166, v197
	ds_read_b64 v[60:61], v60
	ds_read_b64 v[62:63], v62
	v_add_u32_e32 v64, v169, v198
	v_add_u32_e32 v66, v169, v199
	s_waitcnt lgkmcnt(2)
	v_mfma_f32_16x16x32_bf16 v[56:59], v[56:59], v[48:51], v[76:79]
	ds_read_b64 v[64:65], v64
	ds_read_b64 v[66:67], v66
	s_waitcnt lgkmcnt(2)
	v_mfma_f32_16x16x32_bf16 v[60:63], v[60:63], v[48:51], v[80:83]
	v_add_u32_e32 v76, v174, v196
	v_add_u32_e32 v78, v174, v197
	s_nop 0
	v_add_u32_e32 v80, v175, v198
	v_mfma_f32_16x16x32_bf16 v[68:71], v[68:71], v[48:51], v[72:75]
	v_add_u32_e32 v82, v175, v199
	ds_read_b64 v[76:77], v76
	ds_read_b64 v[78:79], v78
	v_add_u32_e32 v72, v173, v194
	v_add_u32_e32 v74, v173, v195
	ds_read_b64 v[72:73], v72
	ds_read_b64 v[74:75], v74
	ds_read_b64 v[80:81], v80
	ds_read_b64 v[82:83], v82
	s_waitcnt lgkmcnt(0)
	s_barrier
	ds_write_b128 v200, v[4:7] offset:34816
	ds_write_b128 v201, v[12:15]
	ds_write_b128 v202, v[8:11] offset:34816
	ds_write_b128 v203, v[16:19]
	ds_write_b128 v205, v[24:27] offset:34816
	ds_write_b128 v206, v[20:23]
	ds_write_b128 v207, v[32:35] offset:34816
	ds_write_b128 v208, v[36:39]
	s_waitcnt lgkmcnt(0)
	s_barrier
	ds_read_b128 v[4:7], v209 offset:34816
	ds_read_b128 v[8:11], v210
	s_waitcnt lgkmcnt(1)
	v_mfma_f32_16x16x32_bf16 v[12:15], v[4:7], v[44:47], 0
	s_waitcnt lgkmcnt(0)
	v_mfma_f32_16x16x32_bf16 v[16:19], v[8:11], v[44:47], 0
	ds_read_b128 v[4:7], v209 offset:39168
	ds_read_b128 v[8:11], v211
	s_waitcnt lgkmcnt(1)
	v_mfma_f32_16x16x32_bf16 v[32:35], v[4:7], v[44:47], 0
	s_waitcnt lgkmcnt(0)
	v_mfma_f32_16x16x32_bf16 v[36:39], v[8:11], v[44:47], 0
	ds_read_b128 v[4:7], v209 offset:43520
	ds_read_b128 v[8:11], v212
	v_mfma_f32_16x16x32_bf16 v[72:75], v[72:75], v[48:51], v[88:91]
	v_mfma_f32_16x16x32_bf16 v[76:79], v[76:79], v[48:51], v[92:95]
	s_waitcnt lgkmcnt(1)
	v_mfma_f32_16x16x32_bf16 v[88:91], v[4:7], v[44:47], 0
	s_waitcnt lgkmcnt(0)
	v_mfma_f32_16x16x32_bf16 v[92:95], v[8:11], v[44:47], 0
	ds_read_b128 v[4:7], v209 offset:47872
	ds_read_b128 v[8:11], v213
	v_mfma_f32_16x16x32_bf16 v[64:67], v[64:67], v[48:51], v[84:87]
	v_mfma_f32_16x16x32_bf16 v[48:51], v[80:83], v[48:51], v[232:235]
	s_waitcnt lgkmcnt(1)
	v_mfma_f32_16x16x32_bf16 v[232:235], v[4:7], v[44:47], 0
	s_waitcnt lgkmcnt(0)
	v_mfma_f32_16x16x32_bf16 v[236:239], v[8:11], v[44:47], 0
	ds_read_b128 v[4:7], v209 offset:52224
	ds_read_b128 v[8:11], v214
	s_waitcnt lgkmcnt(1)
	v_mfma_f32_16x16x32_bf16 v[240:243], v[4:7], v[44:47], 0
	s_waitcnt lgkmcnt(0)
	v_mfma_f32_16x16x32_bf16 v[244:247], v[8:11], v[44:47], 0
	ds_read_b128 v[4:7], v209 offset:56576
	ds_read_b128 v[8:11], v215
	s_waitcnt lgkmcnt(1)
	v_mfma_f32_16x16x32_bf16 v[80:83], v[4:7], v[44:47], 0
	s_waitcnt lgkmcnt(0)
	v_mfma_f32_16x16x32_bf16 v[84:87], v[8:11], v[44:47], 0
	ds_read_b128 v[4:7], v209 offset:60928
	ds_read_b128 v[8:11], v216
	s_waitcnt lgkmcnt(1)
	v_mfma_f32_16x16x32_bf16 v[20:23], v[4:7], v[44:47], 0
	ds_read_b128 v[4:7], v209 offset:65280
	ds_read_b128 v[248:251], v217
	s_waitcnt lgkmcnt(2)
	v_mfma_f32_16x16x32_bf16 v[24:27], v[8:11], v[44:47], 0
	s_waitcnt lgkmcnt(1)
	v_mfma_f32_16x16x32_bf16 v[8:11], v[4:7], v[44:47], 0
	s_waitcnt lgkmcnt(0)
	v_mfma_f32_16x16x32_bf16 v[4:7], v[248:251], v[44:47], 0
	ds_read_b128 v[44:47], v209 offset:34880
	ds_read_b128 v[248:251], v210 offset:64
	s_waitcnt lgkmcnt(1)
	v_mfma_f32_16x16x32_bf16 v[12:15], v[44:47], v[40:43], v[12:15]
	s_waitcnt lgkmcnt(0)
; #define LAS __attribute__((address_space(3)))
; #define MFMA16(a, b, c) __builtin_amdgcn_mfma_f32_16x16x32_bf16((a), (b), (c), 0, 0, 0)
; __device__ __forceinline__ void ret_unit(LAS unsigned char* lds, int u, const bf16* PROJ, const int* pos, const float* dec_f, const float* dec_b, const bf16* ST,
;                                          const float* gn_w, const float* gn_b, bf16* MIX, int tid, const WsRef& wsr) {
;     ...
;         for (int kk = 0; kk < 4; ++kk)
; #pragma unroll
;             for (int n = 0; n < 8; ++n) { const bf16x8 yf = *(const LAS bf16x8*)(Ks + (n * 16 + fr) * LDT + kk * 32 + fq * 8); const bf16x8 yb = *(const LAS bf16x8*)(VT + (n * 16 + fr) * LDT + kk * 32 + fq * 8);
;                 tf[n] = MFMA16(yf, qf[kk], tf[n]); tb[n] = MFMA16(yb, qf[kk], tb[n]); }
	v_mfma_f32_16x16x32_bf16 v[16:19], v[248:251], v[40:43], v[16:19]
	ds_read_b128 v[44:47], v209 offset:39232
	ds_read_b128 v[248:251], v211 offset:64
	s_waitcnt lgkmcnt(1)
	v_mfma_f32_16x16x32_bf16 v[32:35], v[44:47], v[40:43], v[32:35]
	s_waitcnt lgkmcnt(0)
	v_mfma_f32_16x16x32_bf16 v[36:39], v[248:251], v[40:43], v[36:39]
	ds_read_b128 v[44:47], v209 offset:43584
	ds_read_b128 v[248:251], v212 offset:64
	s_waitcnt lgkmcnt(1)
	v_mfma_f32_16x16x32_bf16 v[44:47], v[44:47], v[40:43], v[88:91]
	s_waitcnt lgkmcnt(0)
	v_mfma_f32_16x16x32_bf16 v[88:91], v[248:251], v[40:43], v[92:95]
	s_nop 2
	ds_read_b128 v[92:95], v209 offset:47936
	ds_read_b128 v[248:251], v213 offset:64
	s_waitcnt lgkmcnt(1)
	v_mfma_f32_16x16x32_bf16 v[92:95], v[92:95], v[40:43], v[232:235]
	s_waitcnt lgkmcnt(0)
	v_mfma_f32_16x16x32_bf16 v[232:235], v[248:251], v[40:43], v[236:239]
	s_nop 2
	ds_read_b128 v[236:239], v209 offset:52288
	ds_read_b128 v[248:251], v214 offset:64
	s_waitcnt lgkmcnt(1)
	v_mfma_f32_16x16x32_bf16 v[236:239], v[236:239], v[40:43], v[240:243]
	s_waitcnt lgkmcnt(0)
	v_mfma_f32_16x16x32_bf16 v[240:243], v[248:251], v[40:43], v[244:247]
	s_nop 2
	ds_read_b128 v[244:247], v209 offset:56640
	ds_read_b128 v[248:251], v215 offset:64
	s_waitcnt lgkmcnt(1)
	v_mfma_f32_16x16x32_bf16 v[80:83], v[244:247], v[40:43], v[80:83]
	s_waitcnt lgkmcnt(0)
	v_mfma_f32_16x16x32_bf16 v[84:87], v[248:251], v[40:43], v[84:87]
	ds_read_b128 v[244:247], v209 offset:60992
	ds_read_b128 v[248:251], v216 offset:64
	s_waitcnt lgkmcnt(1)
	v_mfma_f32_16x16x32_bf16 v[244:247], v[244:247], v[40:43], v[20:23]
	s_waitcnt lgkmcnt(0)
	v_mfma_f32_16x16x32_bf16 v[248:251], v[248:251], v[40:43], v[24:27]
	s_nop 0
	ds_read_b128 v[20:23], v209 offset:65344
	s_nop 0
	ds_read_b128 v[24:27], v217 offset:64
	s_waitcnt lgkmcnt(1)
	v_mfma_f32_16x16x32_bf16 v[8:11], v[20:23], v[40:43], v[8:11]
	s_waitcnt lgkmcnt(0)
	v_mfma_f32_16x16x32_bf16 v[4:7], v[24:27], v[40:43], v[4:7]
	ds_read_b128 v[20:23], v209 offset:34944
	ds_read_b128 v[24:27], v210 offset:128
	s_waitcnt lgkmcnt(1)
	v_mfma_f32_16x16x32_bf16 v[40:43], v[20:23], v[28:31], v[12:15]
	s_waitcnt lgkmcnt(0)
	v_mfma_f32_16x16x32_bf16 v[130:133], v[24:27], v[28:31], v[16:19]
	s_nop 0
	ds_read_b128 v[12:15], v209 offset:39296
	s_nop 0
	ds_read_b128 v[16:19], v211 offset:128
	s_waitcnt lgkmcnt(1)
	v_mfma_f32_16x16x32_bf16 v[32:35], v[12:15], v[28:31], v[32:35]
	s_waitcnt lgkmcnt(0)
	v_mfma_f32_16x16x32_bf16 v[36:39], v[16:19], v[28:31], v[36:39]
	ds_read_b128 v[12:15], v209 offset:43648
	ds_read_b128 v[16:19], v212 offset:128
	s_waitcnt lgkmcnt(1)
	v_mfma_f32_16x16x32_bf16 v[44:47], v[12:15], v[28:31], v[44:47]
	s_waitcnt lgkmcnt(0)
	v_mfma_f32_16x16x32_bf16 v[88:91], v[16:19], v[28:31], v[88:91]
	ds_read_b128 v[12:15], v209 offset:48000
	ds_read_b128 v[16:19], v213 offset:128
	s_waitcnt lgkmcnt(1)
	v_mfma_f32_16x16x32_bf16 v[92:95], v[12:15], v[28:31], v[92:95]
	s_waitcnt lgkmcnt(0)
	v_mfma_f32_16x16x32_bf16 v[232:235], v[16:19], v[28:31], v[232:235]
	ds_read_b128 v[12:15], v209 offset:52352
	ds_read_b128 v[16:19], v214 offset:128
	s_waitcnt lgkmcnt(1)
	v_mfma_f32_16x16x32_bf16 v[236:239], v[12:15], v[28:31], v[236:239]
	s_waitcnt lgkmcnt(0)
	v_mfma_f32_16x16x32_bf16 v[240:243], v[16:19], v[28:31], v[240:243]
	ds_read_b128 v[12:15], v209 offset:56704
	ds_read_b128 v[16:19], v215 offset:128
	s_waitcnt lgkmcnt(1)
	v_mfma_f32_16x16x32_bf16 v[20:23], v[12:15], v[28:31], v[80:83]
	s_waitcnt lgkmcnt(0)
	v_mfma_f32_16x16x32_bf16 v[24:27], v[16:19], v[28:31], v[84:87]
	ds_read_b128 v[12:15], v209 offset:61056
	ds_read_b128 v[16:19], v216 offset:128
	ds_read_b128 v[80:83], v209 offset:65408
	ds_read_b128 v[84:87], v217 offset:128
	s_waitcnt lgkmcnt(3)
	v_mfma_f32_16x16x32_bf16 v[12:15], v[12:15], v[28:31], v[244:247]
	s_waitcnt lgkmcnt(2)
	v_mfma_f32_16x16x32_bf16 v[16:19], v[16:19], v[28:31], v[248:251]
	s_waitcnt lgkmcnt(1)
	v_mfma_f32_16x16x32_bf16 v[8:11], v[80:83], v[28:31], v[8:11]
	s_waitcnt lgkmcnt(0)
	v_mfma_f32_16x16x32_bf16 v[4:7], v[84:87], v[28:31], v[4:7]
	ds_read_b128 v[28:31], v209 offset:35008
	ds_read_b128 v[80:83], v210 offset:192
	s_waitcnt lgkmcnt(1)
	v_mfma_f32_16x16x32_bf16 v[28:31], v[28:31], v[0:3], v[40:43]
	s_waitcnt lgkmcnt(0)
	v_mfma_f32_16x16x32_bf16 v[40:43], v[80:83], v[0:3], v[130:133]
	ds_read_b128 v[80:83], v209 offset:39360
	ds_read_b128 v[84:87], v211 offset:192
	s_waitcnt lgkmcnt(1)
	v_mfma_f32_16x16x32_bf16 v[80:83], v[80:83], v[0:3], v[32:35]
	s_waitcnt lgkmcnt(0)
	v_mfma_f32_16x16x32_bf16 v[34:37], v[84:87], v[0:3], v[36:39]
	ds_read_b128 v[84:87], v209 offset:43712
	ds_read_b128 v[130:133], v212 offset:192
	s_waitcnt lgkmcnt(1)
	v_mfma_f32_16x16x32_bf16 v[44:47], v[84:87], v[0:3], v[44:47]
	s_waitcnt lgkmcnt(0)
	v_mfma_f32_16x16x32_bf16 v[84:87], v[130:133], v[0:3], v[88:91]
	s_nop 2
	ds_read_b128 v[88:91], v209 offset:48064
	ds_read_b128 v[130:133], v213 offset:192
	s_waitcnt lgkmcnt(1)
	v_mfma_f32_16x16x32_bf16 v[88:91], v[88:91], v[0:3], v[92:95]
	s_waitcnt lgkmcnt(0)
	v_mfma_f32_16x16x32_bf16 v[92:95], v[130:133], v[0:3], v[232:235]
	ds_read_b128 v[130:133], v209 offset:52416
	s_nop 1
	ds_read_b128 v[232:235], v214 offset:192
	s_waitcnt lgkmcnt(1)
	v_mfma_f32_16x16x32_bf16 v[130:133], v[130:133], v[0:3], v[236:239]
	s_waitcnt lgkmcnt(0)
	v_mfma_f32_16x16x32_bf16 v[232:235], v[232:235], v[0:3], v[240:243]
	s_nop 0
	ds_read_b128 v[236:239], v209 offset:56768
	s_nop 0
	ds_read_b128 v[240:243], v215 offset:192
	s_waitcnt lgkmcnt(1)
	v_mfma_f32_16x16x32_bf16 v[236:239], v[236:239], v[0:3], v[20:23]
	s_waitcnt lgkmcnt(0)
	v_mfma_f32_16x16x32_bf16 v[240:243], v[240:243], v[0:3], v[24:27]
	s_nop 0
	ds_read_b128 v[20:23], v209 offset:61120
	s_nop 0
	ds_read_b128 v[24:27], v216 offset:192
	s_waitcnt lgkmcnt(1)
; #define LAS __attribute__((address_space(3)))
; __device__ __forceinline__ float fexp2(float x) { return __builtin_amdgcn_exp2f(x); }
; #define MFMA16(a, b, c) __builtin_amdgcn_mfma_f32_16x16x32_bf16((a), (b), (c), 0, 0, 0)
; __device__ __forceinline__ void ret_unit(LAS unsigned char* lds, int u, const bf16* PROJ, const int* pos, const float* dec_f, const float* dec_b, const bf16* ST,
;                                          const float* gn_w, const float* gn_b, bf16* MIX, int tid, const WsRef& wsr) {
;     ...
;         for (int kk = 0; kk < 4; ++kk)
; #pragma unroll
;             for (int n = 0; n < 8; ++n) { const bf16x8 yf = *(const LAS bf16x8*)(Ks + (n * 16 + fr) * LDT + kk * 32 + fq * 8); const bf16x8 yb = *(const LAS bf16x8*)(VT + (n * 16 + fr) * LDT + kk * 32 + fq * 8);
;                 tf[n] = MFMA16(yf, qf[kk], tf[n]); tb[n] = MFMA16(yb, qf[kk], tb[n]); }
;         const float xif = fexp2(lgf2 * (float)(q + 1)), xib = fexp2(lgb2 * (float)(128 - q));
; #pragma unroll
;         for (int n = 0; n < 8; ++n) o[n] = o[n] + tf[n] * xif + tb[n] * xib;
;     }
;     float sm = 0.f;
; #pragma unroll
;     for (int n = 0; n < 8; ++n) sm += (o[n][0] + o[n][1]) + (o[n][2] + o[n][3]);
;     sm += __shfl_xor(sm, 16); sm += __shfl_xor(sm, 32);
	v_mfma_f32_16x16x32_bf16 v[12:15], v[20:23], v[0:3], v[12:15]
	s_waitcnt lgkmcnt(0)
	v_mfma_f32_16x16x32_bf16 v[244:247], v[24:27], v[0:3], v[16:19]
	s_nop 2
	ds_read_b128 v[16:19], v209 offset:65472
	ds_read_b128 v[20:23], v217 offset:192
	s_waitcnt lgkmcnt(1)
	v_mfma_f32_16x16x32_bf16 v[8:11], v[16:19], v[0:3], v[8:11]
	s_waitcnt lgkmcnt(0)
	v_mfma_f32_16x16x32_bf16 v[248:251], v[20:23], v[0:3], v[4:7]
	v_mul_f32_e32 v0, v105, v218
	v_exp_f32_e32 v38, v0
	v_mul_f32_e32 v0, v230, v219
	v_exp_f32_e32 v230, v0
	v_pk_fma_f32 v[2:3], v[38:39], v[28:29], v[52:53] op_sel_hi:[0,1,1]
	v_pk_fma_f32 v[16:17], v[38:39], v[132:133], v[70:71] op_sel_hi:[0,1,1]
	v_pk_fma_f32 v[0:1], v[38:39], v[30:31], v[54:55] op_sel_hi:[0,1,1]
	v_pk_fma_f32 v[32:33], v[230:231], v[40:41], v[2:3] op_sel_hi:[0,1,1]
	v_pk_fma_f32 v[2:3], v[38:39], v[80:81], v[56:57] op_sel_hi:[0,1,1]
	v_pk_fma_f32 v[18:19], v[38:39], v[130:131], v[68:69] op_sel_hi:[0,1,1]
	v_pk_fma_f32 v[22:23], v[230:231], v[234:235], v[16:17] op_sel_hi:[0,1,1]
	v_pk_fma_f32 v[16:17], v[38:39], v[238:239], v[74:75] op_sel_hi:[0,1,1]
	v_pk_fma_f32 v[12:13], v[38:39], v[12:13], v[76:77] op_sel_hi:[0,1,1]
	v_pk_fma_f32 v[30:31], v[230:231], v[42:43], v[0:1] op_sel_hi:[0,1,1]
	v_pk_fma_f32 v[0:1], v[38:39], v[82:83], v[58:59] op_sel_hi:[0,1,1]
	v_pk_fma_f32 v[28:29], v[230:231], v[34:35], v[2:3] op_sel_hi:[0,1,1]
	v_pk_fma_f32 v[24:25], v[230:231], v[232:233], v[18:19] op_sel_hi:[0,1,1]
	v_pk_fma_f32 v[18:19], v[230:231], v[242:243], v[16:17] op_sel_hi:[0,1,1]
	v_pk_fma_f32 v[16:17], v[230:231], v[244:245], v[12:13] op_sel_hi:[0,1,1]
	v_pk_fma_f32 v[10:11], v[38:39], v[10:11], v[50:51] op_sel_hi:[0,1,1]
	v_pk_fma_f32 v[12:13], v[38:39], v[8:9], v[48:49] op_sel_hi:[0,1,1]
	v_pk_fma_f32 v[26:27], v[230:231], v[36:37], v[0:1] op_sel_hi:[0,1,1]
	v_pk_fma_f32 v[8:9], v[230:231], v[250:251], v[10:11] op_sel_hi:[0,1,1]
	v_pk_fma_f32 v[10:11], v[230:231], v[248:249], v[12:13] op_sel_hi:[0,1,1]
	v_mov_b32_e32 v12, v32
	v_mov_b32_e32 v13, v28
	v_mov_b32_e32 v34, v33
	v_mov_b32_e32 v35, v29
	v_pk_fma_f32 v[0:1], v[38:39], v[46:47], v[62:63] op_sel_hi:[0,1,1]
	v_pk_fma_f32 v[2:3], v[38:39], v[44:45], v[60:61] op_sel_hi:[0,1,1]
	v_pk_add_f32 v[12:13], v[12:13], v[34:35]
	v_mov_b32_e32 v34, v30
	v_mov_b32_e32 v35, v26
	v_mov_b32_e32 v36, v31
	v_mov_b32_e32 v37, v27
	v_pk_fma_f32 v[4:5], v[230:231], v[86:87], v[0:1] op_sel_hi:[0,1,1]
	v_pk_fma_f32 v[6:7], v[230:231], v[84:85], v[2:3] op_sel_hi:[0,1,1]
	v_pk_add_f32 v[34:35], v[34:35], v[36:37]
	v_mov_b32_e32 v36, v6
	v_pk_add_f32 v[12:13], v[12:13], v[34:35]
	v_pk_mov_b32 v[34:35], v[6:7], v[4:5] op_sel:[1,0]
	v_mov_b32_e32 v37, v5
	v_pk_fma_f32 v[0:1], v[38:39], v[90:91], v[66:67] op_sel_hi:[0,1,1]
	v_pk_fma_f32 v[2:3], v[38:39], v[88:89], v[64:65] op_sel_hi:[0,1,1]
	v_pk_add_f32 v[34:35], v[34:35], v[36:37]
	v_pk_fma_f32 v[0:1], v[230:231], v[94:95], v[0:1] op_sel_hi:[0,1,1]
	v_pk_fma_f32 v[2:3], v[230:231], v[92:93], v[2:3] op_sel_hi:[0,1,1]
	v_add_f32_e32 v12, 0, v12
	v_pk_add_f32 v[34:35], v[34:35], v[34:35] op_sel:[0,1] op_sel_hi:[1,0]
	v_pk_fma_f32 v[20:21], v[38:39], v[236:237], v[72:73] op_sel_hi:[0,1,1]
	v_pk_fma_f32 v[14:15], v[38:39], v[14:15], v[78:79] op_sel_hi:[0,1,1]
	v_add_f32_e32 v12, v12, v13
	v_add_f32_e32 v36, v2, v3
	v_add_f32_e32 v38, v0, v1
	v_mov_b32_e32 v13, v24
	v_mov_b32_e32 v35, v25
	v_mov_b32_e32 v37, v22
	v_mov_b32_e32 v39, v23
	v_pk_fma_f32 v[20:21], v[230:231], v[240:241], v[20:21] op_sel_hi:[0,1,1]
	v_pk_add_f32 v[12:13], v[12:13], v[34:35]
	v_pk_add_f32 v[34:35], v[36:37], v[38:39]
	v_mov_b32_e32 v36, v20
	v_pk_add_f32 v[12:13], v[12:13], v[34:35]
	v_pk_mov_b32 v[34:35], v[20:21], v[18:19] op_sel:[1,0]
	v_mov_b32_e32 v37, v19
	v_pk_add_f32 v[34:35], v[34:35], v[36:37]
	v_pk_fma_f32 v[14:15], v[230:231], v[246:247], v[14:15] op_sel_hi:[0,1,1]
	v_pk_add_f32 v[12:13], v[12:13], v[12:13] op_sel:[0,1] op_sel_hi:[1,0]
	v_pk_add_f32 v[34:35], v[34:35], v[34:35] op_sel:[0,1] op_sel_hi:[1,0]
	v_add_f32_e32 v36, v16, v17
	v_add_f32_e32 v38, v14, v15
	v_mov_b32_e32 v13, v10
	v_mov_b32_e32 v35, v11
	v_mov_b32_e32 v37, v8
	v_mov_b32_e32 v39, v9
	v_pk_add_f32 v[12:13], v[12:13], v[34:35]
	v_pk_add_f32 v[34:35], v[36:37], v[38:39]
	v_or_b32_e32 v48, s0, v126
	v_pk_add_f32 v[12:13], v[12:13], v[34:35]
	v_mov_b32_e32 v49, v97
	v_add_f32_e32 v12, v12, v13
	ds_bpermute_b32 v13, v220, v12
	s_waitcnt lgkmcnt(0)
	v_add_f32_e32 v12, v12, v13
	ds_bpermute_b32 v13, v221, v12
	s_waitcnt lgkmcnt(0)
; __device__ __forceinline__ unsigned pk2(float lo, float hi) { return pg8::cvt_pk_bf16(lo, hi); }
; __device__ __forceinline__ float bflo(unsigned w) { return __uint_as_float(w << 16); }
; __device__ __forceinline__ float bfhi(unsigned w) { return __uint_as_float(w & 0xffff0000u); }
; __device__ __forceinline__ void ret_unit(LAS unsigned char* lds, int u, const bf16* PROJ, const int* pos, const float* dec_f, const float* dec_b, const bf16* ST,
;                                          const float* gn_w, const float* gn_b, bf16* MIX, int tid, const WsRef& wsr) {
;     ...
;     float sm = 0.f;
; #pragma unroll
;     for (int n = 0; n < 8; ++n) sm += (o[n][0] + o[n][1]) + (o[n][2] + o[n][3]);
;     sm += __shfl_xor(sm, 16); sm += __shfl_xor(sm, 32);
;     const float mu = sm * (1.f / 128.f);
;     float vq = 0.f;
; #pragma unroll
;     for (int n = 0; n < 8; ++n) { const f32x4 d = o[n] - mu; vq += (d[0] * d[0] + d[1] * d[1]) + (d[2] * d[2] + d[3] * d[3]); }
;     vq += __shfl_xor(vq, 16); vq += __shfl_xor(vq, 32);
;     const float rstd = rsqrtf(vq * (1.f / 128.f) + EPS);
;     const size_t row = row0 + q;
; #pragma unroll
;     for (int n = 0; n < 8; ++n) { const int col = h * 128 + n * 16 + 4 * fq;
;         const f32x4 gw = *(const f32x4*)(gn_w + col), gb = *(const f32x4*)(gn_b + col);
;         const u32x2 gg = *(const u32x2*)(PROJ + row * INC + 1536 + col);
;         const f32x4 g = (f32x4){bflo(gg.x), bfhi(gg.x), bflo(gg.y), bfhi(gg.y)};
;         f32x4 y = (o[n] - mu) * rstd * gw + gb;
; #pragma unroll
;         for (int r = 0; r < 4; ++r) y[r] = y[r] * g[r] * __builtin_amdgcn_rcpf(1.f + __expf(-g[r]));
;         u32x2 w; w.x = pk2(y[0], y[1]); w.y = pk2(y[2], y[3]); *(u32x2*)(MIX + row * D + col) = w; }
	v_add_f32_e32 v40, v12, v13
	v_fmamk_f32 v33, v40, 0xbc000000, v33
	v_fmamk_f32 v29, v40, 0xbc000000, v29
	v_fmamk_f32 v31, v40, 0xbc000000, v31
	v_fmac_f32_e32 v32, 0xbc000000, v40
	v_fmamk_f32 v27, v40, 0xbc000000, v27
	v_fmac_f32_e32 v28, 0xbc000000, v40
	v_mov_b32_e32 v34, v33
	v_mov_b32_e32 v35, v29
	v_fmac_f32_e32 v30, 0xbc000000, v40
	v_fmac_f32_e32 v26, 0xbc000000, v40
	v_mov_b32_e32 v12, v32
	v_mov_b32_e32 v13, v28
	v_pk_mul_f32 v[34:35], v[34:35], v[34:35]
	v_mov_b32_e32 v36, v31
	v_mov_b32_e32 v37, v27
	v_pk_fma_f32 v[12:13], v[12:13], v[12:13], v[34:35]
	v_mov_b32_e32 v34, v30
	v_mov_b32_e32 v35, v26
	v_pk_mul_f32 v[36:37], v[36:37], v[36:37]
	v_fmamk_f32 v7, v40, 0xbc000000, v7
	v_pk_fma_f32 v[34:35], v[34:35], v[34:35], v[36:37]
	v_fmac_f32_e32 v6, 0xbc000000, v40
	v_pk_add_f32 v[12:13], v[12:13], v[34:35]
	v_fmamk_f32 v5, v40, 0xbc000000, v5
	v_fmac_f32_e32 v4, 0xbc000000, v40
	v_pk_add_f32 v[12:13], v[12:13], v[12:13] op_sel_hi:[0,1]
	v_pk_mul_f32 v[34:35], v[4:5], v[4:5]
	v_pk_mul_f32 v[36:37], v[6:7], v[6:7]
	v_fmac_f32_e32 v2, 0xbc000000, v40
	v_pk_mov_b32 v[38:39], v[36:37], v[34:35] op_sel:[1,0]
	v_mov_b32_e32 v37, v35
	v_fmamk_f32 v3, v40, 0xbc000000, v3
	v_fmac_f32_e32 v0, 0xbc000000, v40
	v_mul_f32_e32 v12, v2, v2
	v_pk_add_f32 v[34:35], v[38:39], v[36:37]
	v_fmamk_f32 v1, v40, 0xbc000000, v1
	v_pk_fma_f32 v[36:37], v[2:3], v[2:3], v[12:13] op_sel_hi:[1,1,0]
	v_mul_f32_e32 v12, v0, v0
	v_pk_add_f32 v[34:35], v[34:35], v[34:35] op_sel_hi:[0,1]
	v_pk_fma_f32 v[38:39], v[0:1], v[0:1], v[12:13] op_sel_hi:[1,1,0]
	v_fmamk_f32 v23, v40, 0xbc000000, v23
	v_fmac_f32_e32 v22, 0xbc000000, v40
	v_fmamk_f32 v25, v40, 0xbc000000, v25
	v_fmac_f32_e32 v24, 0xbc000000, v40
	v_mul_f32_e32 v36, v24, v24
	v_mul_f32_e32 v38, v25, v25
	v_mul_f32_e32 v34, v22, v22
	v_mul_f32_e32 v12, v23, v23
	v_pk_add_f32 v[36:37], v[36:37], v[38:39]
	v_pk_add_f32 v[12:13], v[34:35], v[12:13]
	v_fmamk_f32 v21, v40, 0xbc000000, v21
	v_pk_add_f32 v[12:13], v[36:37], v[12:13]
	v_fmac_f32_e32 v20, 0xbc000000, v40
	v_fmamk_f32 v19, v40, 0xbc000000, v19
	v_fmac_f32_e32 v18, 0xbc000000, v40
	v_pk_add_f32 v[12:13], v[12:13], v[12:13] op_sel_hi:[0,1]
	v_pk_mul_f32 v[34:35], v[18:19], v[18:19]
	v_pk_mul_f32 v[36:37], v[20:21], v[20:21]
	v_fmac_f32_e32 v16, 0xbc000000, v40
	v_pk_mov_b32 v[38:39], v[36:37], v[34:35] op_sel:[1,0]
	v_mov_b32_e32 v37, v35
	v_fmamk_f32 v17, v40, 0xbc000000, v17
	v_fmac_f32_e32 v14, 0xbc000000, v40
	v_mul_f32_e32 v12, v16, v16
	v_pk_add_f32 v[34:35], v[38:39], v[36:37]
	v_fmamk_f32 v15, v40, 0xbc000000, v15
	v_pk_fma_f32 v[36:37], v[16:17], v[16:17], v[12:13] op_sel_hi:[1,1,0]
	v_mul_f32_e32 v12, v14, v14
	v_pk_add_f32 v[34:35], v[34:35], v[34:35] op_sel_hi:[0,1]
	v_pk_fma_f32 v[38:39], v[14:15], v[14:15], v[12:13] op_sel_hi:[1,1,0]
	v_fmamk_f32 v9, v40, 0xbc000000, v9
	v_fmac_f32_e32 v8, 0xbc000000, v40
	v_fmamk_f32 v11, v40, 0xbc000000, v11
	v_fmac_f32_e32 v10, 0xbc000000, v40
	v_mul_f32_e32 v36, v10, v10
	v_mul_f32_e32 v38, v11, v11
	v_mul_f32_e32 v34, v8, v8
	v_mul_f32_e32 v12, v9, v9
	v_pk_add_f32 v[36:37], v[36:37], v[38:39]
	v_pk_add_f32 v[12:13], v[34:35], v[12:13]
	v_lshl_add_u64 v[34:35], s[4:5], 0, v[102:103]
	v_pk_add_f32 v[12:13], v[36:37], v[12:13]
	v_mov_b64_e32 v[36:37], s[6:7]
	v_add_f32_e32 v12, v12, v13
	ds_bpermute_b32 v13, v220, v12
	s_waitcnt lgkmcnt(0)
	v_add_f32_e32 v12, v12, v13
	ds_bpermute_b32 v13, v221, v12
	s_waitcnt lgkmcnt(0)
	v_add_f32_e32 v12, v12, v13
	v_fmamk_f32 v12, v12, 0x3c000000, v227
	v_cmp_gt_f32_e64 s[68:69], s1, v12
	v_mul_f32_e32 v13, 0x4b800000, v12
	v_mad_u64_u32 v[44:45], s[0:1], v34, s72, v[36:37]
	v_cndmask_b32_e64 v12, v12, v13, s[68:69]
	v_rsq_f32_e32 v12, v12
	v_mad_i32_i24 v45, v35, s72, v45
	v_lshlrev_b64 v[34:35], 11, v[34:35]
	v_lshl_add_u64 v[46:47], s[70:71], 0, v[34:35]
	v_mul_f32_e32 v13, 0x45800000, v12
	v_cndmask_b32_e64 v12, v12, v13, s[68:69]
	v_lshlrev_b32_e32 v13, 2, v48
	v_lshlrev_b32_e32 v48, 1, v48
	v_lshl_add_u64 v[34:35], v[44:45], 0, v[48:49]
	v_lshl_add_u64 v[46:47], v[46:47], 0, v[48:49]
	global_load_dwordx2 v[56:57], v[34:35], off offset:3072
	global_load_dwordx2 v[58:59], v[34:35], off offset:3104
	global_load_dwordx2 v[60:61], v[34:35], off offset:3136
	global_load_dwordx2 v[62:63], v[34:35], off offset:3168
	global_load_dwordx2 v[64:65], v[34:35], off offset:3200
	global_load_dwordx2 v[66:67], v[34:35], off offset:3232
	global_load_dwordx2 v[68:69], v[34:35], off offset:3264
	global_load_dwordx2 v[70:71], v[34:35], off offset:3296
	global_load_dwordx4 v[72:75], v13, s[22:23]
	global_load_dwordx4 v[76:79], v13, s[36:37]
	global_load_dwordx4 v[80:83], v13, s[22:23] offset:64
	global_load_dwordx4 v[84:87], v13, s[36:37] offset:64
	global_load_dwordx4 v[88:91], v13, s[22:23] offset:128
	global_load_dwordx4 v[92:95], v13, s[36:37] offset:128
	global_load_dwordx4 v[36:39], v13, s[22:23] offset:192
	global_load_dwordx4 v[40:43], v13, s[36:37] offset:192
	global_load_dwordx4 v[232:235], v13, s[22:23] offset:256
	global_load_dwordx4 v[236:239], v13, s[36:37] offset:256
	global_load_dwordx4 v[240:243], v13, s[22:23] offset:320
	global_load_dwordx4 v[248:251], v13, s[36:37] offset:320
	v_pk_mul_f32 v[32:33], v[32:33], v[12:13] op_sel_hi:[1,0]
	v_pk_mul_f32 v[30:31], v[30:31], v[12:13] op_sel_hi:[1,0]
	v_pk_mul_f32 v[28:29], v[28:29], v[12:13] op_sel_hi:[1,0]
	v_pk_mul_f32 v[26:27], v[26:27], v[12:13] op_sel_hi:[1,0]
	v_pk_mul_f32 v[6:7], v[6:7], v[12:13] op_sel_hi:[1,0]
	v_pk_mul_f32 v[4:5], v[4:5], v[12:13] op_sel_hi:[1,0]
	v_pk_mul_f32 v[2:3], v[2:3], v[12:13] op_sel_hi:[1,0]
	v_pk_mul_f32 v[0:1], v[0:1], v[12:13] op_sel_hi:[1,0]
	v_pk_mul_f32 v[24:25], v[24:25], v[12:13] op_sel_hi:[1,0]
	v_pk_mul_f32 v[22:23], v[22:23], v[12:13] op_sel_hi:[1,0]
	v_pk_mul_f32 v[20:21], v[20:21], v[12:13] op_sel_hi:[1,0]
	v_pk_mul_f32 v[18:19], v[18:19], v[12:13] op_sel_hi:[1,0]
	v_pk_mul_f32 v[16:17], v[16:17], v[12:13] op_sel_hi:[1,0]
	v_pk_mul_f32 v[14:15], v[14:15], v[12:13] op_sel_hi:[1,0]
	v_pk_mul_f32 v[10:11], v[10:11], v[12:13] op_sel_hi:[1,0]
	v_pk_mul_f32 v[8:9], v[8:9], v[12:13] op_sel_hi:[1,0]
	s_waitcnt vmcnt(10)
; __device__ __forceinline__ unsigned pk2(float lo, float hi) { return pg8::cvt_pk_bf16(lo, hi); }
; __device__ __forceinline__ float bflo(unsigned w) { return __uint_as_float(w << 16); }
; __device__ __forceinline__ float bfhi(unsigned w) { return __uint_as_float(w & 0xffff0000u); }
; __device__ __forceinline__ void ret_unit(LAS unsigned char* lds, int u, const bf16* PROJ, const int* pos, const float* dec_f, const float* dec_b, const bf16* ST,
;                                          const float* gn_w, const float* gn_b, bf16* MIX, int tid, const WsRef& wsr) {
;     ...
;     const size_t row = row0 + q;
; #pragma unroll
;     for (int n = 0; n < 8; ++n) { const int col = h * 128 + n * 16 + 4 * fq;
;         const f32x4 gw = *(const f32x4*)(gn_w + col), gb = *(const f32x4*)(gn_b + col);
;         const u32x2 gg = *(const u32x2*)(PROJ + row * INC + 1536 + col);
;         const f32x4 g = (f32x4){bflo(gg.x), bfhi(gg.x), bflo(gg.y), bfhi(gg.y)};
;         f32x4 y = (o[n] - mu) * rstd * gw + gb;
; #pragma unroll
;         for (int r = 0; r < 4; ++r) y[r] = y[r] * g[r] * __builtin_amdgcn_rcpf(1.f + __expf(-g[r]));
;         u32x2 w; w.x = pk2(y[0], y[1]); w.y = pk2(y[2], y[3]); *(u32x2*)(MIX + row * D + col) = w; }
	v_lshlrev_b32_e32 v130, 16, v56
	v_and_b32_e32 v131, 0xffff0000, v56
	v_lshlrev_b32_e32 v132, 16, v57
	v_and_b32_e32 v133, 0xffff0000, v57
	v_pk_fma_f32 v[32:33], v[72:73], v[32:33], v[76:77]
	v_pk_fma_f32 v[30:31], v[74:75], v[30:31], v[78:79]
	global_load_dwordx4 v[72:75], v13, s[22:23] offset:384
	global_load_dwordx4 v[76:79], v13, s[36:37] offset:384
	v_mul_f32_e32 v56, 0xbfb8aa3b, v130
	v_mul_f32_e32 v57, 0xbfb8aa3b, v131
	v_exp_f32_e32 v56, v56
	v_exp_f32_e32 v57, v57
	v_pk_mul_f32 v[32:33], v[32:33], v[130:131]
	v_mul_f32_e32 v130, 0xbfb8aa3b, v132
	v_mul_f32_e32 v131, 0xbfb8aa3b, v133
	v_add_f32_e32 v56, 1.0, v56
	v_add_f32_e32 v57, 1.0, v57
	v_rcp_f32_e32 v56, v56
	v_rcp_f32_e32 v57, v57
	v_exp_f32_e32 v130, v130
	v_exp_f32_e32 v131, v131
	v_pk_mul_f32 v[30:31], v[30:31], v[132:133]
	v_pk_mul_f32 v[32:33], v[56:57], v[32:33]
	v_add_f32_e32 v130, 1.0, v130
	v_add_f32_e32 v131, 1.0, v131
	v_rcp_f32_e32 v130, v130
	v_rcp_f32_e32 v131, v131
	v_cvt_pk_bf16_f32 v56, v32, v33
	s_nop 0
	v_pk_mul_f32 v[30:31], v[130:131], v[30:31]
	s_nop 0
	v_cvt_pk_bf16_f32 v57, v30, v31
	global_store_dwordx2 v[46:47], v[56:57], off
	s_waitcnt vmcnt(11)
	v_lshlrev_b32_e32 v130, 16, v58
	v_and_b32_e32 v131, 0xffff0000, v58
	v_lshlrev_b32_e32 v132, 16, v59
	v_and_b32_e32 v133, 0xffff0000, v59
	v_pk_fma_f32 v[28:29], v[80:81], v[28:29], v[84:85]
	v_pk_fma_f32 v[26:27], v[82:83], v[26:27], v[86:87]
	global_load_dwordx4 v[80:83], v13, s[22:23] offset:448
	global_load_dwordx4 v[84:87], v13, s[36:37] offset:448
	v_mul_f32_e32 v58, 0xbfb8aa3b, v130
	v_mul_f32_e32 v59, 0xbfb8aa3b, v131
	v_exp_f32_e32 v58, v58
	v_exp_f32_e32 v59, v59
	v_pk_mul_f32 v[28:29], v[28:29], v[130:131]
	v_mul_f32_e32 v130, 0xbfb8aa3b, v132
	v_mul_f32_e32 v131, 0xbfb8aa3b, v133
	v_add_f32_e32 v58, 1.0, v58
	v_add_f32_e32 v59, 1.0, v59
	v_rcp_f32_e32 v58, v58
	v_rcp_f32_e32 v59, v59
	v_exp_f32_e32 v130, v130
	v_exp_f32_e32 v131, v131
	v_pk_mul_f32 v[26:27], v[26:27], v[132:133]
	v_pk_mul_f32 v[28:29], v[58:59], v[28:29]
	v_add_f32_e32 v130, 1.0, v130
	v_add_f32_e32 v131, 1.0, v131
	v_rcp_f32_e32 v130, v130
	v_rcp_f32_e32 v131, v131
	v_cvt_pk_bf16_f32 v58, v28, v29
	s_nop 0
	v_pk_mul_f32 v[26:27], v[130:131], v[26:27]
	s_nop 0
	v_cvt_pk_bf16_f32 v59, v26, v27
	global_store_dwordx2 v[46:47], v[58:59], off offset:32
	s_waitcnt vmcnt(12)
	v_lshlrev_b32_e32 v130, 16, v60
	v_and_b32_e32 v131, 0xffff0000, v60
	v_lshlrev_b32_e32 v132, 16, v61
	v_and_b32_e32 v133, 0xffff0000, v61
	v_pk_fma_f32 v[6:7], v[88:89], v[6:7], v[92:93]
	v_pk_fma_f32 v[4:5], v[90:91], v[4:5], v[94:95]
	v_mul_f32_e32 v60, 0xbfb8aa3b, v130
	v_mul_f32_e32 v61, 0xbfb8aa3b, v131
	v_exp_f32_e32 v60, v60
	v_exp_f32_e32 v61, v61
	v_pk_mul_f32 v[6:7], v[6:7], v[130:131]
	v_mul_f32_e32 v130, 0xbfb8aa3b, v132
	v_mul_f32_e32 v131, 0xbfb8aa3b, v133
	v_add_f32_e32 v60, 1.0, v60
	v_add_f32_e32 v61, 1.0, v61
	v_rcp_f32_e32 v60, v60
	v_rcp_f32_e32 v61, v61
	v_exp_f32_e32 v130, v130
	v_exp_f32_e32 v131, v131
	v_pk_mul_f32 v[4:5], v[4:5], v[132:133]
	v_pk_mul_f32 v[6:7], v[60:61], v[6:7]
	v_add_f32_e32 v130, 1.0, v130
	v_add_f32_e32 v131, 1.0, v131
	v_rcp_f32_e32 v130, v130
	v_rcp_f32_e32 v131, v131
	v_cvt_pk_bf16_f32 v60, v6, v7
	s_nop 0
	v_pk_mul_f32 v[4:5], v[130:131], v[4:5]
	s_nop 0
	v_cvt_pk_bf16_f32 v61, v4, v5
	global_store_dwordx2 v[46:47], v[60:61], off offset:64
	s_waitcnt vmcnt(11)
	v_lshlrev_b32_e32 v130, 16, v62
	v_and_b32_e32 v131, 0xffff0000, v62
	v_lshlrev_b32_e32 v132, 16, v63
	v_and_b32_e32 v133, 0xffff0000, v63
	v_pk_fma_f32 v[2:3], v[36:37], v[2:3], v[40:41]
	v_pk_fma_f32 v[0:1], v[38:39], v[0:1], v[42:43]
	v_mul_f32_e32 v62, 0xbfb8aa3b, v130
	v_mul_f32_e32 v63, 0xbfb8aa3b, v131
	v_exp_f32_e32 v62, v62
	v_exp_f32_e32 v63, v63
	v_pk_mul_f32 v[2:3], v[2:3], v[130:131]
	v_mul_f32_e32 v130, 0xbfb8aa3b, v132
	v_mul_f32_e32 v131, 0xbfb8aa3b, v133
	v_add_f32_e32 v62, 1.0, v62
	v_add_f32_e32 v63, 1.0, v63
	v_rcp_f32_e32 v62, v62
	v_rcp_f32_e32 v63, v63
	v_exp_f32_e32 v130, v130
	v_exp_f32_e32 v131, v131
	v_pk_mul_f32 v[0:1], v[0:1], v[132:133]
	v_pk_mul_f32 v[2:3], v[62:63], v[2:3]
	v_add_f32_e32 v130, 1.0, v130
	v_add_f32_e32 v131, 1.0, v131
	v_rcp_f32_e32 v130, v130
	v_rcp_f32_e32 v131, v131
	v_cvt_pk_bf16_f32 v62, v2, v3
	s_nop 0
	v_pk_mul_f32 v[0:1], v[130:131], v[0:1]
	s_nop 0
	v_cvt_pk_bf16_f32 v63, v0, v1
	global_store_dwordx2 v[46:47], v[62:63], off offset:96
	s_waitcnt vmcnt(10)
; __device__ __forceinline__ unsigned pk2(float lo, float hi) { return pg8::cvt_pk_bf16(lo, hi); }
; __device__ __forceinline__ float bflo(unsigned w) { return __uint_as_float(w << 16); }
; __device__ __forceinline__ float bfhi(unsigned w) { return __uint_as_float(w & 0xffff0000u); }
; __device__ __forceinline__ void ret_unit(LAS unsigned char* lds, int u, const bf16* PROJ, const int* pos, const float* dec_f, const float* dec_b, const bf16* ST,
;                                          const float* gn_w, const float* gn_b, bf16* MIX, int tid, const WsRef& wsr) {
;     ...
;     const size_t row = row0 + q;
; #pragma unroll
;     for (int n = 0; n < 8; ++n) { const int col = h * 128 + n * 16 + 4 * fq;
;         const f32x4 gw = *(const f32x4*)(gn_w + col), gb = *(const f32x4*)(gn_b + col);
;         const u32x2 gg = *(const u32x2*)(PROJ + row * INC + 1536 + col);
;         const f32x4 g = (f32x4){bflo(gg.x), bfhi(gg.x), bflo(gg.y), bfhi(gg.y)};
;         f32x4 y = (o[n] - mu) * rstd * gw + gb;
; #pragma unroll
;         for (int r = 0; r < 4; ++r) y[r] = y[r] * g[r] * __builtin_amdgcn_rcpf(1.f + __expf(-g[r]));
;         u32x2 w; w.x = pk2(y[0], y[1]); w.y = pk2(y[2], y[3]); *(u32x2*)(MIX + row * D + col) = w; }
;     __syncthreads();
	v_lshlrev_b32_e32 v130, 16, v64
	v_and_b32_e32 v131, 0xffff0000, v64
	v_lshlrev_b32_e32 v132, 16, v65
	v_and_b32_e32 v133, 0xffff0000, v65
	v_pk_fma_f32 v[24:25], v[232:233], v[24:25], v[236:237]
	v_pk_fma_f32 v[22:23], v[234:235], v[22:23], v[238:239]
	v_mul_f32_e32 v64, 0xbfb8aa3b, v130
	v_mul_f32_e32 v65, 0xbfb8aa3b, v131
	v_exp_f32_e32 v64, v64
	v_exp_f32_e32 v65, v65
	v_pk_mul_f32 v[24:25], v[24:25], v[130:131]
	v_mul_f32_e32 v130, 0xbfb8aa3b, v132
	v_mul_f32_e32 v131, 0xbfb8aa3b, v133
	v_add_f32_e32 v64, 1.0, v64
	v_add_f32_e32 v65, 1.0, v65
	v_rcp_f32_e32 v64, v64
	v_rcp_f32_e32 v65, v65
	v_exp_f32_e32 v130, v130
	v_exp_f32_e32 v131, v131
	v_pk_mul_f32 v[22:23], v[22:23], v[132:133]
	v_pk_mul_f32 v[24:25], v[64:65], v[24:25]
	v_add_f32_e32 v130, 1.0, v130
	v_add_f32_e32 v131, 1.0, v131
	v_rcp_f32_e32 v130, v130
	v_rcp_f32_e32 v131, v131
	v_cvt_pk_bf16_f32 v64, v24, v25
	s_nop 0
	v_pk_mul_f32 v[22:23], v[130:131], v[22:23]
	s_nop 0
	v_cvt_pk_bf16_f32 v65, v22, v23
	global_store_dwordx2 v[46:47], v[64:65], off offset:128
	s_waitcnt vmcnt(9)
	v_lshlrev_b32_e32 v130, 16, v66
	v_and_b32_e32 v131, 0xffff0000, v66
	v_lshlrev_b32_e32 v132, 16, v67
	v_and_b32_e32 v133, 0xffff0000, v67
	v_pk_fma_f32 v[20:21], v[240:241], v[20:21], v[248:249]
	v_pk_fma_f32 v[18:19], v[242:243], v[18:19], v[250:251]
	v_mul_f32_e32 v66, 0xbfb8aa3b, v130
	v_mul_f32_e32 v67, 0xbfb8aa3b, v131
	v_exp_f32_e32 v66, v66
	v_exp_f32_e32 v67, v67
	v_pk_mul_f32 v[20:21], v[20:21], v[130:131]
	v_mul_f32_e32 v130, 0xbfb8aa3b, v132
	v_mul_f32_e32 v131, 0xbfb8aa3b, v133
	v_add_f32_e32 v66, 1.0, v66
	v_add_f32_e32 v67, 1.0, v67
	v_rcp_f32_e32 v66, v66
	v_rcp_f32_e32 v67, v67
	v_exp_f32_e32 v130, v130
	v_exp_f32_e32 v131, v131
	v_pk_mul_f32 v[18:19], v[18:19], v[132:133]
	v_pk_mul_f32 v[20:21], v[66:67], v[20:21]
	v_add_f32_e32 v130, 1.0, v130
	v_add_f32_e32 v131, 1.0, v131
	v_rcp_f32_e32 v130, v130
	v_rcp_f32_e32 v131, v131
	v_cvt_pk_bf16_f32 v66, v20, v21
	s_nop 0
	v_pk_mul_f32 v[18:19], v[130:131], v[18:19]
	s_nop 0
	v_cvt_pk_bf16_f32 v67, v18, v19
	global_store_dwordx2 v[46:47], v[66:67], off offset:160
	s_waitcnt vmcnt(8)
	v_lshlrev_b32_e32 v130, 16, v68
	v_and_b32_e32 v131, 0xffff0000, v68
	v_lshlrev_b32_e32 v132, 16, v69
	v_and_b32_e32 v133, 0xffff0000, v69
	v_pk_fma_f32 v[16:17], v[72:73], v[16:17], v[76:77]
	v_pk_fma_f32 v[14:15], v[74:75], v[14:15], v[78:79]
	v_mul_f32_e32 v68, 0xbfb8aa3b, v130
	v_mul_f32_e32 v69, 0xbfb8aa3b, v131
	v_exp_f32_e32 v68, v68
	v_exp_f32_e32 v69, v69
	v_pk_mul_f32 v[16:17], v[16:17], v[130:131]
	v_mul_f32_e32 v130, 0xbfb8aa3b, v132
	v_mul_f32_e32 v131, 0xbfb8aa3b, v133
	v_add_f32_e32 v68, 1.0, v68
	v_add_f32_e32 v69, 1.0, v69
	v_rcp_f32_e32 v68, v68
	v_rcp_f32_e32 v69, v69
	v_exp_f32_e32 v130, v130
	v_exp_f32_e32 v131, v131
	v_pk_mul_f32 v[14:15], v[14:15], v[132:133]
	v_pk_mul_f32 v[16:17], v[68:69], v[16:17]
	v_add_f32_e32 v130, 1.0, v130
	v_add_f32_e32 v131, 1.0, v131
	v_rcp_f32_e32 v130, v130
	v_rcp_f32_e32 v131, v131
	v_cvt_pk_bf16_f32 v68, v16, v17
	s_nop 0
	v_pk_mul_f32 v[14:15], v[130:131], v[14:15]
	s_nop 0
	v_cvt_pk_bf16_f32 v69, v14, v15
	global_store_dwordx2 v[46:47], v[68:69], off offset:192
	s_waitcnt vmcnt(6)
	v_lshlrev_b32_e32 v130, 16, v70
	v_and_b32_e32 v131, 0xffff0000, v70
	v_lshlrev_b32_e32 v132, 16, v71
	v_and_b32_e32 v133, 0xffff0000, v71
	v_pk_fma_f32 v[10:11], v[80:81], v[10:11], v[84:85]
	v_pk_fma_f32 v[8:9], v[82:83], v[8:9], v[86:87]
	v_mul_f32_e32 v70, 0xbfb8aa3b, v130
	v_mul_f32_e32 v71, 0xbfb8aa3b, v131
	v_exp_f32_e32 v70, v70
	v_exp_f32_e32 v71, v71
	v_pk_mul_f32 v[10:11], v[10:11], v[130:131]
	v_mul_f32_e32 v130, 0xbfb8aa3b, v132
	v_mul_f32_e32 v131, 0xbfb8aa3b, v133
	v_add_f32_e32 v70, 1.0, v70
	v_add_f32_e32 v71, 1.0, v71
	v_rcp_f32_e32 v70, v70
	v_rcp_f32_e32 v71, v71
	v_exp_f32_e32 v130, v130
	v_exp_f32_e32 v131, v131
	v_pk_mul_f32 v[8:9], v[8:9], v[132:133]
	v_pk_mul_f32 v[10:11], v[70:71], v[10:11]
	v_add_f32_e32 v130, 1.0, v130
	v_add_f32_e32 v131, 1.0, v131
	v_rcp_f32_e32 v130, v130
	v_rcp_f32_e32 v131, v131
	v_cvt_pk_bf16_f32 v70, v10, v11
	s_nop 0
	v_pk_mul_f32 v[8:9], v[130:131], v[8:9]
	s_nop 0
	v_cvt_pk_bf16_f32 v71, v8, v9
	global_store_dwordx2 v[46:47], v[70:71], off offset:224
	s_barrier
	s_cbranch_scc1 .LBB0_438
	v_readlane_b32 s82, v255, 40
	v_readlane_b32 s4, v255, 38
	v_readlane_b32 s80, v255, 42
	v_readlane_b32 s83, v255, 41
	v_readlane_b32 s5, v255, 39
	v_readlane_b32 s2, v255, 58
	v_readlane_b32 s81, v255, 43
